# static priority: per-MFMA-block s_setprio flips deleted in the four multi-unit GEMM K-loops, trailing half-workgroup (waves 4-7) raised to priority 1 for the K-loop
# speedup vs baseline: 1.0112x; 1.0001x over previous
.Ltb_g3_skip:
	s_andn2_b64 vcc, exec, s[50:51]
	s_cbranch_vccnz .Lprio_g3_done
	s_setprio 1

.Lpw0_done:
	s_waitcnt lgkmcnt(0)
	s_barrier
	s_waitcnt lgkmcnt(0)
	v_mfma_f32_16x16x32_bf16 v[126:129], v[140:143], v[198:201], 0
	v_mfma_f32_16x16x32_bf16 v[122:125], v[154:157], v[198:201], 0
	v_mfma_f32_16x16x32_bf16 v[118:121], v[140:143], v[214:217], 0
	v_mfma_f32_16x16x32_bf16 v[114:117], v[154:157], v[214:217], 0
	v_mfma_f32_16x16x32_bf16 v[110:113], v[140:143], v[222:225], 0
	v_mfma_f32_16x16x32_bf16 v[106:109], v[154:157], v[222:225], 0
	v_mfma_f32_16x16x32_bf16 v[102:105], v[140:143], v[230:233], 0
	v_mfma_f32_16x16x32_bf16 v[98:101], v[154:157], v[230:233], 0
	v_mfma_f32_16x16x32_bf16 v[126:129], v[150:153], v[202:205], v[126:129]
	v_mfma_f32_16x16x32_bf16 v[122:125], v[158:161], v[202:205], v[122:125]
	v_mfma_f32_16x16x32_bf16 v[118:121], v[150:153], v[218:221], v[118:121]
	v_mfma_f32_16x16x32_bf16 v[114:117], v[158:161], v[218:221], v[114:117]
	v_mfma_f32_16x16x32_bf16 v[110:113], v[150:153], v[226:229], v[110:113]
	v_mfma_f32_16x16x32_bf16 v[106:109], v[158:161], v[226:229], v[106:109]
	v_mfma_f32_16x16x32_bf16 v[102:105], v[150:153], v[234:237], v[102:105]
	v_mfma_f32_16x16x32_bf16 v[98:101], v[158:161], v[234:237], v[98:101]
	v_mfma_f32_16x16x32_bf16 v[94:97], v[176:179], v[198:201], 0
	v_mfma_f32_16x16x32_bf16 v[90:93], v[184:187], v[198:201], 0
	v_mfma_f32_16x16x32_bf16 v[86:89], v[176:179], v[214:217], 0
	v_mfma_f32_16x16x32_bf16 v[82:85], v[184:187], v[214:217], 0
	v_mfma_f32_16x16x32_bf16 v[78:81], v[176:179], v[222:225], 0
	v_mfma_f32_16x16x32_bf16 v[74:77], v[184:187], v[222:225], 0
	v_mfma_f32_16x16x32_bf16 v[70:73], v[176:179], v[230:233], 0
	v_mfma_f32_16x16x32_bf16 v[66:69], v[184:187], v[230:233], 0
	v_mfma_f32_16x16x32_bf16 v[94:97], v[180:183], v[202:205], v[94:97]
	v_mfma_f32_16x16x32_bf16 v[90:93], v[194:197], v[202:205], v[90:93]
	v_mfma_f32_16x16x32_bf16 v[86:89], v[180:183], v[218:221], v[86:89]
	v_mfma_f32_16x16x32_bf16 v[82:85], v[194:197], v[218:221], v[82:85]
	v_mfma_f32_16x16x32_bf16 v[78:81], v[180:183], v[226:229], v[78:81]
	v_mfma_f32_16x16x32_bf16 v[74:77], v[194:197], v[226:229], v[74:77]
	v_mfma_f32_16x16x32_bf16 v[70:73], v[180:183], v[234:237], v[70:73]
	v_mfma_f32_16x16x32_bf16 v[66:69], v[194:197], v[234:237], v[66:69]
	s_barrier
	s_add_i32 s2, s16, s20
	v_lshl_add_u64 v[144:145], v[136:137], 0, v[164:165]
	s_mov_b32 m0, s2
	ds_read_b128 v[198:201], v191 offset:16384
	ds_read_b128 v[202:205], v191 offset:17408
	ds_read_b128 v[214:217], v191 offset:18432
	ds_read_b128 v[218:221], v191 offset:19456
	ds_read_b128 v[222:225], v191 offset:20480
	ds_read_b128 v[226:229], v191 offset:21504
	ds_read_b128 v[230:233], v191 offset:22528
	ds_read_b128 v[234:237], v191 offset:23552
	global_load_lds_dwordx4 v[144:145], off
	v_lshl_add_u64 v[166:167], v[136:137], 0, v[174:175]
	s_add_i32 m0, s2, 0x2000
	v_lshl_add_u64 v[238:239], v[136:137], 0, s[18:19]
	s_add_i32 s2, vcc_lo, s20
	global_load_lds_dwordx4 v[166:167], off
	v_lshl_add_u64 v[240:241], v[238:239], 0, v[164:165]
	s_mov_b32 m0, s2
	v_lshl_add_u64 v[238:239], v[238:239], 0, v[174:175]
	global_load_lds_dwordx4 v[240:241], off
	s_add_i32 m0, s2, 0x2000
	v_lshl_add_u64 v[240:241], s[86:87], 0, v[172:173]
	global_load_lds_dwordx4 v[238:239], off
	v_lshl_add_u64 v[238:239], s[86:87], 0, v[162:163]
	s_mov_b32 m0, s21
	s_nop 0
	global_load_lds_dwordx4 v[238:239], off
	s_mov_b32 m0, s23
	s_nop 0
	global_load_lds_dwordx4 v[240:241], off
	s_cmp_eq_u32 s41, 0
	s_cbranch_scc1 .Lpw1_first
	s_waitcnt vmcnt(16)
	s_branch .Lpw1_done

.Lpw1_done:
	s_waitcnt lgkmcnt(0)
	s_barrier
	s_waitcnt lgkmcnt(0)
	v_mfma_f32_16x16x32_bf16 v[62:65], v[140:143], v[198:201], 0
	v_mfma_f32_16x16x32_bf16 v[58:61], v[154:157], v[198:201], 0
	v_mfma_f32_16x16x32_bf16 v[54:57], v[140:143], v[214:217], 0
	v_mfma_f32_16x16x32_bf16 v[50:53], v[154:157], v[214:217], 0
	v_mfma_f32_16x16x32_bf16 v[46:49], v[140:143], v[222:225], 0
	v_mfma_f32_16x16x32_bf16 v[42:45], v[154:157], v[222:225], 0
	v_mfma_f32_16x16x32_bf16 v[38:41], v[140:143], v[230:233], 0
	v_mfma_f32_16x16x32_bf16 v[34:37], v[154:157], v[230:233], 0
	v_mfma_f32_16x16x32_bf16 v[62:65], v[150:153], v[202:205], v[62:65]
	v_mfma_f32_16x16x32_bf16 v[58:61], v[158:161], v[202:205], v[58:61]
	v_mfma_f32_16x16x32_bf16 v[54:57], v[150:153], v[218:221], v[54:57]
	v_mfma_f32_16x16x32_bf16 v[50:53], v[158:161], v[218:221], v[50:53]
	v_mfma_f32_16x16x32_bf16 v[46:49], v[150:153], v[226:229], v[46:49]
	v_mfma_f32_16x16x32_bf16 v[42:45], v[158:161], v[226:229], v[42:45]
	v_mfma_f32_16x16x32_bf16 v[38:41], v[150:153], v[234:237], v[38:41]
	v_mfma_f32_16x16x32_bf16 v[34:37], v[158:161], v[234:237], v[34:37]
	v_mfma_f32_16x16x32_bf16 v[30:33], v[176:179], v[198:201], 0
	v_mfma_f32_16x16x32_bf16 v[26:29], v[184:187], v[198:201], 0
	v_mfma_f32_16x16x32_bf16 v[22:25], v[176:179], v[214:217], 0
	v_mfma_f32_16x16x32_bf16 v[18:21], v[184:187], v[214:217], 0
	v_mfma_f32_16x16x32_bf16 v[14:17], v[176:179], v[222:225], 0
	v_mfma_f32_16x16x32_bf16 v[10:13], v[184:187], v[222:225], 0
	v_mfma_f32_16x16x32_bf16 v[6:9], v[176:179], v[230:233], 0
	v_mfma_f32_16x16x32_bf16 v[2:5], v[184:187], v[230:233], 0
	v_mfma_f32_16x16x32_bf16 v[30:33], v[180:183], v[202:205], v[30:33]
	v_mfma_f32_16x16x32_bf16 v[26:29], v[194:197], v[202:205], v[26:29]
	v_mfma_f32_16x16x32_bf16 v[22:25], v[180:183], v[218:221], v[22:25]
	v_mfma_f32_16x16x32_bf16 v[18:21], v[194:197], v[218:221], v[18:21]
	v_mfma_f32_16x16x32_bf16 v[14:17], v[180:183], v[226:229], v[14:17]
	v_mfma_f32_16x16x32_bf16 v[10:13], v[194:197], v[226:229], v[10:13]
	v_mfma_f32_16x16x32_bf16 v[6:9], v[180:183], v[234:237], v[6:9]
	v_mfma_f32_16x16x32_bf16 v[2:5], v[194:197], v[234:237], v[2:5]
	s_barrier
	s_add_i32 s16, 0, 0x18000
	v_add_u32_e32 v139, s16, v188
	s_add_i32 s73, 0, 0x1c000
	ds_read_b128 v[140:143], v139
	ds_read_b128 v[150:153], v139 offset:1024
	ds_read_b128 v[154:157], v139 offset:2048
	ds_read_b128 v[158:161], v139 offset:3072
	v_add_u32_e32 v139, s73, v188
	ds_read_b128 v[176:179], v139
	ds_read_b128 v[180:183], v139 offset:1024
	ds_read_b128 v[184:187], v139 offset:2048
	ds_read_b128 v[194:197], v139 offset:3072
	s_add_u32 s2, s86, 0x40000
	s_addc_u32 s3, s87, 0
	s_mov_b32 m0, s26
	v_lshl_add_u64 v[242:243], s[2:3], 0, v[162:163]
	ds_read_b128 v[198:201], v191 offset:32768
	ds_read_b128 v[202:205], v191 offset:33792
	ds_read_b128 v[214:217], v191 offset:34816
	ds_read_b128 v[218:221], v191 offset:35840
	ds_read_b128 v[222:225], v191 offset:36864
	ds_read_b128 v[226:229], v191 offset:37888
	ds_read_b128 v[230:233], v191 offset:38912
	ds_read_b128 v[234:237], v191 offset:39936
	global_load_lds_dwordx4 v[242:243], off
	v_lshl_add_u64 v[242:243], s[2:3], 0, v[172:173]
	s_mov_b32 m0, s27
	s_nop 0
	global_load_lds_dwordx4 v[242:243], off
	s_waitcnt vmcnt(8)
	s_waitcnt lgkmcnt(0)
	s_barrier
	s_waitcnt lgkmcnt(0)
	v_mfma_f32_16x16x32_bf16 v[126:129], v[140:143], v[198:201], v[126:129]
	v_mfma_f32_16x16x32_bf16 v[122:125], v[154:157], v[198:201], v[122:125]
	v_mfma_f32_16x16x32_bf16 v[118:121], v[140:143], v[214:217], v[118:121]
	v_mfma_f32_16x16x32_bf16 v[114:117], v[154:157], v[214:217], v[114:117]
	v_mfma_f32_16x16x32_bf16 v[110:113], v[140:143], v[222:225], v[110:113]
	v_mfma_f32_16x16x32_bf16 v[106:109], v[154:157], v[222:225], v[106:109]
	v_mfma_f32_16x16x32_bf16 v[102:105], v[140:143], v[230:233], v[102:105]
	v_mfma_f32_16x16x32_bf16 v[98:101], v[154:157], v[230:233], v[98:101]
	v_mfma_f32_16x16x32_bf16 v[126:129], v[150:153], v[202:205], v[126:129]
	v_mfma_f32_16x16x32_bf16 v[122:125], v[158:161], v[202:205], v[122:125]
	v_mfma_f32_16x16x32_bf16 v[118:121], v[150:153], v[218:221], v[118:121]
	v_mfma_f32_16x16x32_bf16 v[114:117], v[158:161], v[218:221], v[114:117]
	v_mfma_f32_16x16x32_bf16 v[110:113], v[150:153], v[226:229], v[110:113]
	v_mfma_f32_16x16x32_bf16 v[106:109], v[158:161], v[226:229], v[106:109]
	v_mfma_f32_16x16x32_bf16 v[102:105], v[150:153], v[234:237], v[102:105]
	v_mfma_f32_16x16x32_bf16 v[98:101], v[158:161], v[234:237], v[98:101]
	v_mfma_f32_16x16x32_bf16 v[94:97], v[176:179], v[198:201], v[94:97]
	v_mfma_f32_16x16x32_bf16 v[90:93], v[184:187], v[198:201], v[90:93]
	v_mfma_f32_16x16x32_bf16 v[86:89], v[176:179], v[214:217], v[86:89]
	v_mfma_f32_16x16x32_bf16 v[82:85], v[184:187], v[214:217], v[82:85]
	v_mfma_f32_16x16x32_bf16 v[78:81], v[176:179], v[222:225], v[78:81]
	v_mfma_f32_16x16x32_bf16 v[74:77], v[184:187], v[222:225], v[74:77]
	v_mfma_f32_16x16x32_bf16 v[70:73], v[176:179], v[230:233], v[70:73]
	v_mfma_f32_16x16x32_bf16 v[66:69], v[184:187], v[230:233], v[66:69]
	v_mfma_f32_16x16x32_bf16 v[94:97], v[180:183], v[202:205], v[94:97]
	v_mfma_f32_16x16x32_bf16 v[90:93], v[194:197], v[202:205], v[90:93]
	v_mfma_f32_16x16x32_bf16 v[86:89], v[180:183], v[218:221], v[86:89]
	v_mfma_f32_16x16x32_bf16 v[82:85], v[194:197], v[218:221], v[82:85]
	v_mfma_f32_16x16x32_bf16 v[78:81], v[180:183], v[226:229], v[78:81]
	v_mfma_f32_16x16x32_bf16 v[74:77], v[194:197], v[226:229], v[74:77]
	v_mfma_f32_16x16x32_bf16 v[70:73], v[180:183], v[234:237], v[70:73]
	v_mfma_f32_16x16x32_bf16 v[66:69], v[194:197], v[234:237], v[66:69]
	s_barrier
	s_add_i32 s2, s16, s20
	v_lshl_add_u64 v[144:145], v[144:145], 0, s[14:15]
	s_mov_b32 m0, s2
	ds_read_b128 v[198:201], v191 offset:49152
	ds_read_b128 v[202:205], v191 offset:50176
	ds_read_b128 v[214:217], v191 offset:51200
	ds_read_b128 v[218:221], v191 offset:52224
	ds_read_b128 v[222:225], v191 offset:53248
	ds_read_b128 v[226:229], v191 offset:54272
	ds_read_b128 v[230:233], v191 offset:55296
	ds_read_b128 v[234:237], v191 offset:56320
	global_load_lds_dwordx4 v[144:145], off
	s_add_i32 m0, s2, 0x2000
	s_mov_b64 s[2:3], 0x40080
	v_lshl_add_u64 v[144:145], v[166:167], 0, s[14:15]
	v_lshl_add_u64 v[136:137], v[136:137], 0, s[2:3]
	s_add_i32 s2, s73, s20
	global_load_lds_dwordx4 v[144:145], off
	v_lshl_add_u64 v[144:145], v[136:137], 0, v[164:165]
	s_mov_b32 m0, s2
	v_lshl_add_u64 v[136:137], v[136:137], 0, v[174:175]
	global_load_lds_dwordx4 v[144:145], off
	s_add_i32 m0, s2, 0x2000
	s_nop 0
	global_load_lds_dwordx4 v[136:137], off
	v_lshl_add_u64 v[136:137], v[238:239], 0, s[14:15]
	s_mov_b32 m0, s91
	s_nop 0
	global_load_lds_dwordx4 v[136:137], off
	v_lshl_add_u64 v[136:137], v[240:241], 0, s[14:15]
	s_mov_b32 m0, s92
	s_nop 0
	global_load_lds_dwordx4 v[136:137], off
	s_waitcnt vmcnt(8)
	s_waitcnt lgkmcnt(0)
	s_barrier
	s_waitcnt lgkmcnt(0)
	v_mfma_f32_16x16x32_bf16 v[62:65], v[140:143], v[198:201], v[62:65]
	v_mfma_f32_16x16x32_bf16 v[58:61], v[154:157], v[198:201], v[58:61]
	v_mfma_f32_16x16x32_bf16 v[54:57], v[140:143], v[214:217], v[54:57]
	v_mfma_f32_16x16x32_bf16 v[50:53], v[154:157], v[214:217], v[50:53]
	v_mfma_f32_16x16x32_bf16 v[46:49], v[140:143], v[222:225], v[46:49]
	v_mfma_f32_16x16x32_bf16 v[42:45], v[154:157], v[222:225], v[42:45]
	v_mfma_f32_16x16x32_bf16 v[38:41], v[140:143], v[230:233], v[38:41]
	v_mfma_f32_16x16x32_bf16 v[34:37], v[154:157], v[230:233], v[34:37]
	v_mfma_f32_16x16x32_bf16 v[62:65], v[150:153], v[202:205], v[62:65]
	v_mfma_f32_16x16x32_bf16 v[58:61], v[158:161], v[202:205], v[58:61]
	v_mfma_f32_16x16x32_bf16 v[54:57], v[150:153], v[218:221], v[54:57]
	v_mfma_f32_16x16x32_bf16 v[50:53], v[158:161], v[218:221], v[50:53]
	v_mfma_f32_16x16x32_bf16 v[46:49], v[150:153], v[226:229], v[46:49]
	v_mfma_f32_16x16x32_bf16 v[42:45], v[158:161], v[226:229], v[42:45]
	v_mfma_f32_16x16x32_bf16 v[38:41], v[150:153], v[234:237], v[38:41]
	v_mfma_f32_16x16x32_bf16 v[34:37], v[158:161], v[234:237], v[34:37]
	v_mfma_f32_16x16x32_bf16 v[30:33], v[176:179], v[198:201], v[30:33]
	v_mfma_f32_16x16x32_bf16 v[26:29], v[184:187], v[198:201], v[26:29]
	v_mfma_f32_16x16x32_bf16 v[22:25], v[176:179], v[214:217], v[22:25]
	v_mfma_f32_16x16x32_bf16 v[18:21], v[184:187], v[214:217], v[18:21]
	v_mfma_f32_16x16x32_bf16 v[14:17], v[176:179], v[222:225], v[14:17]
	v_mfma_f32_16x16x32_bf16 v[10:13], v[184:187], v[222:225], v[10:13]
	v_mfma_f32_16x16x32_bf16 v[6:9], v[176:179], v[230:233], v[6:9]
	v_mfma_f32_16x16x32_bf16 v[2:5], v[184:187], v[230:233], v[2:5]
	v_mfma_f32_16x16x32_bf16 v[30:33], v[180:183], v[202:205], v[30:33]
	v_mfma_f32_16x16x32_bf16 v[26:29], v[194:197], v[202:205], v[26:29]
	v_mfma_f32_16x16x32_bf16 v[22:25], v[180:183], v[218:221], v[22:25]
	v_mfma_f32_16x16x32_bf16 v[18:21], v[194:197], v[218:221], v[18:21]
	v_mfma_f32_16x16x32_bf16 v[14:17], v[180:183], v[226:229], v[14:17]
	v_mfma_f32_16x16x32_bf16 v[10:13], v[194:197], v[226:229], v[10:13]
	v_mfma_f32_16x16x32_bf16 v[6:9], v[180:183], v[234:237], v[6:9]
	v_mfma_f32_16x16x32_bf16 v[2:5], v[194:197], v[234:237], v[2:5]
	s_barrier
	s_mov_b32 s34, 2

.LBB0_332:
	s_lshl_b32 s16, s34, 7
	s_add_u32 s73, s8, s16
	s_addc_u32 s75, s9, 0
	s_add_u32 vcc_lo, s73, 0x100
	s_addc_u32 vcc_hi, s75, 0
	s_and_b64 s[86:87], s[2:3], exec
	s_cselect_b32 s87, s5, vcc_hi
	s_cselect_b32 s86, s29, vcc_lo
	v_lshl_add_u64 v[136:137], v[130:131], 0, s[16:17]
	s_mov_b64 vcc, 0x100
	s_add_i32 s16, 0, 0x10000
	v_lshl_add_u64 v[136:137], v[136:137], 0, vcc
	v_add_u32_e32 v139, s16, v188
	s_add_i32 vcc_lo, 0, 0x14000
	ds_read_b128 v[140:143], v139
	ds_read_b128 v[150:153], v139 offset:1024
	ds_read_b128 v[154:157], v139 offset:2048
	ds_read_b128 v[158:161], v139 offset:3072
	v_add_u32_e32 v139, vcc_lo, v188
	ds_read_b128 v[176:179], v139
	ds_read_b128 v[180:183], v139 offset:1024
	ds_read_b128 v[184:187], v139 offset:2048
	ds_read_b128 v[194:197], v139 offset:3072
	v_cndmask_b32_e64 v137, v137, v133, s[2:3]
	v_cndmask_b32_e64 v136, v136, v138, s[2:3]
	s_add_u32 s2, s73, 0x40080
	s_addc_u32 s3, s75, 0
	v_lshl_add_u64 v[144:145], s[2:3], 0, v[162:163]
	s_add_i32 m0, s21, 0xc000
	ds_read_b128 v[198:201], v191
	ds_read_b128 v[202:205], v191 offset:1024
	ds_read_b128 v[214:217], v191 offset:2048
	ds_read_b128 v[218:221], v191 offset:3072
	ds_read_b128 v[222:225], v191 offset:4096
	ds_read_b128 v[226:229], v191 offset:5120
	ds_read_b128 v[230:233], v191 offset:6144
	ds_read_b128 v[234:237], v191 offset:7168
	global_load_lds_dwordx4 v[144:145], off
	v_lshl_add_u64 v[144:145], s[2:3], 0, v[172:173]
	s_add_i32 m0, s21, 0xe000
	s_nop 0
	global_load_lds_dwordx4 v[144:145], off
	s_waitcnt vmcnt(8)
	s_waitcnt lgkmcnt(0)
	s_barrier
	s_waitcnt lgkmcnt(0)
	v_mfma_f32_16x16x32_bf16 v[126:129], v[140:143], v[198:201], v[126:129]
	v_mfma_f32_16x16x32_bf16 v[122:125], v[154:157], v[198:201], v[122:125]
	v_mfma_f32_16x16x32_bf16 v[118:121], v[140:143], v[214:217], v[118:121]
	v_mfma_f32_16x16x32_bf16 v[114:117], v[154:157], v[214:217], v[114:117]
	v_mfma_f32_16x16x32_bf16 v[110:113], v[140:143], v[222:225], v[110:113]
	v_mfma_f32_16x16x32_bf16 v[106:109], v[154:157], v[222:225], v[106:109]
	v_mfma_f32_16x16x32_bf16 v[102:105], v[140:143], v[230:233], v[102:105]
	v_mfma_f32_16x16x32_bf16 v[98:101], v[154:157], v[230:233], v[98:101]
	v_mfma_f32_16x16x32_bf16 v[126:129], v[150:153], v[202:205], v[126:129]
	v_mfma_f32_16x16x32_bf16 v[122:125], v[158:161], v[202:205], v[122:125]
	v_mfma_f32_16x16x32_bf16 v[118:121], v[150:153], v[218:221], v[118:121]
	v_mfma_f32_16x16x32_bf16 v[114:117], v[158:161], v[218:221], v[114:117]
	v_mfma_f32_16x16x32_bf16 v[110:113], v[150:153], v[226:229], v[110:113]
	v_mfma_f32_16x16x32_bf16 v[106:109], v[158:161], v[226:229], v[106:109]
	v_mfma_f32_16x16x32_bf16 v[102:105], v[150:153], v[234:237], v[102:105]
	v_mfma_f32_16x16x32_bf16 v[98:101], v[158:161], v[234:237], v[98:101]
	v_mfma_f32_16x16x32_bf16 v[94:97], v[176:179], v[198:201], v[94:97]
	v_mfma_f32_16x16x32_bf16 v[90:93], v[184:187], v[198:201], v[90:93]
	v_mfma_f32_16x16x32_bf16 v[86:89], v[176:179], v[214:217], v[86:89]
	v_mfma_f32_16x16x32_bf16 v[82:85], v[184:187], v[214:217], v[82:85]
	v_mfma_f32_16x16x32_bf16 v[78:81], v[176:179], v[222:225], v[78:81]
	v_mfma_f32_16x16x32_bf16 v[74:77], v[184:187], v[222:225], v[74:77]
	v_mfma_f32_16x16x32_bf16 v[70:73], v[176:179], v[230:233], v[70:73]
	v_mfma_f32_16x16x32_bf16 v[66:69], v[184:187], v[230:233], v[66:69]
	v_mfma_f32_16x16x32_bf16 v[94:97], v[180:183], v[202:205], v[94:97]
	v_mfma_f32_16x16x32_bf16 v[90:93], v[194:197], v[202:205], v[90:93]
	v_mfma_f32_16x16x32_bf16 v[86:89], v[180:183], v[218:221], v[86:89]
	v_mfma_f32_16x16x32_bf16 v[82:85], v[194:197], v[218:221], v[82:85]
	v_mfma_f32_16x16x32_bf16 v[78:81], v[180:183], v[226:229], v[78:81]
	v_mfma_f32_16x16x32_bf16 v[74:77], v[194:197], v[226:229], v[74:77]
	v_mfma_f32_16x16x32_bf16 v[70:73], v[180:183], v[234:237], v[70:73]
	v_mfma_f32_16x16x32_bf16 v[66:69], v[194:197], v[234:237], v[66:69]
	s_barrier
	s_add_i32 s2, s16, s20
	v_lshl_add_u64 v[144:145], v[136:137], 0, v[164:165]
	s_mov_b32 m0, s2
	ds_read_b128 v[198:201], v191 offset:16384
	ds_read_b128 v[202:205], v191 offset:17408
	ds_read_b128 v[214:217], v191 offset:18432
	ds_read_b128 v[218:221], v191 offset:19456
	ds_read_b128 v[222:225], v191 offset:20480
	ds_read_b128 v[226:229], v191 offset:21504
	ds_read_b128 v[230:233], v191 offset:22528
	ds_read_b128 v[234:237], v191 offset:23552
	global_load_lds_dwordx4 v[144:145], off
	v_lshl_add_u64 v[166:167], v[136:137], 0, v[174:175]
	s_add_i32 m0, s2, 0x2000
	v_lshl_add_u64 v[238:239], v[136:137], 0, s[18:19]
	s_add_i32 s2, vcc_lo, s20
	global_load_lds_dwordx4 v[166:167], off
	v_lshl_add_u64 v[240:241], v[238:239], 0, v[164:165]
	s_mov_b32 m0, s2
	v_lshl_add_u64 v[238:239], v[238:239], 0, v[174:175]
	global_load_lds_dwordx4 v[240:241], off
	s_add_i32 m0, s2, 0x2000
	v_lshl_add_u64 v[240:241], s[86:87], 0, v[172:173]
	global_load_lds_dwordx4 v[238:239], off
	v_lshl_add_u64 v[238:239], s[86:87], 0, v[162:163]
	s_mov_b32 m0, s21
	s_nop 0
	global_load_lds_dwordx4 v[238:239], off
	s_mov_b32 m0, s23
	s_nop 0
	global_load_lds_dwordx4 v[240:241], off
	s_waitcnt vmcnt(8)
	s_waitcnt lgkmcnt(0)
	s_barrier
	s_waitcnt lgkmcnt(0)
	v_mfma_f32_16x16x32_bf16 v[62:65], v[140:143], v[198:201], v[62:65]
	v_mfma_f32_16x16x32_bf16 v[58:61], v[154:157], v[198:201], v[58:61]
	v_mfma_f32_16x16x32_bf16 v[54:57], v[140:143], v[214:217], v[54:57]
	v_mfma_f32_16x16x32_bf16 v[50:53], v[154:157], v[214:217], v[50:53]
	v_mfma_f32_16x16x32_bf16 v[46:49], v[140:143], v[222:225], v[46:49]
	v_mfma_f32_16x16x32_bf16 v[42:45], v[154:157], v[222:225], v[42:45]
	v_mfma_f32_16x16x32_bf16 v[38:41], v[140:143], v[230:233], v[38:41]
	v_mfma_f32_16x16x32_bf16 v[34:37], v[154:157], v[230:233], v[34:37]
	v_mfma_f32_16x16x32_bf16 v[62:65], v[150:153], v[202:205], v[62:65]
	v_mfma_f32_16x16x32_bf16 v[58:61], v[158:161], v[202:205], v[58:61]
	v_mfma_f32_16x16x32_bf16 v[54:57], v[150:153], v[218:221], v[54:57]
	v_mfma_f32_16x16x32_bf16 v[50:53], v[158:161], v[218:221], v[50:53]
	v_mfma_f32_16x16x32_bf16 v[46:49], v[150:153], v[226:229], v[46:49]
	v_mfma_f32_16x16x32_bf16 v[42:45], v[158:161], v[226:229], v[42:45]
	v_mfma_f32_16x16x32_bf16 v[38:41], v[150:153], v[234:237], v[38:41]
	v_mfma_f32_16x16x32_bf16 v[34:37], v[158:161], v[234:237], v[34:37]
	v_mfma_f32_16x16x32_bf16 v[30:33], v[176:179], v[198:201], v[30:33]
	v_mfma_f32_16x16x32_bf16 v[26:29], v[184:187], v[198:201], v[26:29]
	v_mfma_f32_16x16x32_bf16 v[22:25], v[176:179], v[214:217], v[22:25]
	v_mfma_f32_16x16x32_bf16 v[18:21], v[184:187], v[214:217], v[18:21]
	v_mfma_f32_16x16x32_bf16 v[14:17], v[176:179], v[222:225], v[14:17]
	v_mfma_f32_16x16x32_bf16 v[10:13], v[184:187], v[222:225], v[10:13]
	v_mfma_f32_16x16x32_bf16 v[6:9], v[176:179], v[230:233], v[6:9]
	v_mfma_f32_16x16x32_bf16 v[2:5], v[184:187], v[230:233], v[2:5]
	v_mfma_f32_16x16x32_bf16 v[30:33], v[180:183], v[202:205], v[30:33]
	v_mfma_f32_16x16x32_bf16 v[26:29], v[194:197], v[202:205], v[26:29]
	v_mfma_f32_16x16x32_bf16 v[22:25], v[180:183], v[218:221], v[22:25]
	v_mfma_f32_16x16x32_bf16 v[18:21], v[194:197], v[218:221], v[18:21]
	v_mfma_f32_16x16x32_bf16 v[14:17], v[180:183], v[226:229], v[14:17]
	v_mfma_f32_16x16x32_bf16 v[10:13], v[194:197], v[226:229], v[10:13]
	v_mfma_f32_16x16x32_bf16 v[6:9], v[180:183], v[234:237], v[6:9]
	v_mfma_f32_16x16x32_bf16 v[2:5], v[194:197], v[234:237], v[2:5]
	s_barrier
	s_add_i32 s16, 0, 0x18000
	v_add_u32_e32 v139, s16, v188
	s_add_i32 s73, 0, 0x1c000
	ds_read_b128 v[140:143], v139
	ds_read_b128 v[150:153], v139 offset:1024
	ds_read_b128 v[154:157], v139 offset:2048
	ds_read_b128 v[158:161], v139 offset:3072
	v_add_u32_e32 v139, s73, v188
	ds_read_b128 v[176:179], v139
	ds_read_b128 v[180:183], v139 offset:1024
	ds_read_b128 v[184:187], v139 offset:2048
	ds_read_b128 v[194:197], v139 offset:3072
	s_add_u32 s2, s86, 0x40000
	s_addc_u32 s3, s87, 0
	s_mov_b32 m0, s26
	v_lshl_add_u64 v[242:243], s[2:3], 0, v[162:163]
	ds_read_b128 v[198:201], v191 offset:32768
	ds_read_b128 v[202:205], v191 offset:33792
	ds_read_b128 v[214:217], v191 offset:34816
	ds_read_b128 v[218:221], v191 offset:35840
	ds_read_b128 v[222:225], v191 offset:36864
	ds_read_b128 v[226:229], v191 offset:37888
	ds_read_b128 v[230:233], v191 offset:38912
	ds_read_b128 v[234:237], v191 offset:39936
	global_load_lds_dwordx4 v[242:243], off
	v_lshl_add_u64 v[242:243], s[2:3], 0, v[172:173]
	s_mov_b32 m0, s27
	s_nop 0
	global_load_lds_dwordx4 v[242:243], off
	s_waitcnt vmcnt(8)
	s_waitcnt lgkmcnt(0)
	s_barrier
	s_waitcnt lgkmcnt(0)
	v_mfma_f32_16x16x32_bf16 v[126:129], v[140:143], v[198:201], v[126:129]
	v_mfma_f32_16x16x32_bf16 v[122:125], v[154:157], v[198:201], v[122:125]
	v_mfma_f32_16x16x32_bf16 v[118:121], v[140:143], v[214:217], v[118:121]
	v_mfma_f32_16x16x32_bf16 v[114:117], v[154:157], v[214:217], v[114:117]
	v_mfma_f32_16x16x32_bf16 v[110:113], v[140:143], v[222:225], v[110:113]
	v_mfma_f32_16x16x32_bf16 v[106:109], v[154:157], v[222:225], v[106:109]
	v_mfma_f32_16x16x32_bf16 v[102:105], v[140:143], v[230:233], v[102:105]
	v_mfma_f32_16x16x32_bf16 v[98:101], v[154:157], v[230:233], v[98:101]
	v_mfma_f32_16x16x32_bf16 v[126:129], v[150:153], v[202:205], v[126:129]
	v_mfma_f32_16x16x32_bf16 v[122:125], v[158:161], v[202:205], v[122:125]
	v_mfma_f32_16x16x32_bf16 v[118:121], v[150:153], v[218:221], v[118:121]
	v_mfma_f32_16x16x32_bf16 v[114:117], v[158:161], v[218:221], v[114:117]
	v_mfma_f32_16x16x32_bf16 v[110:113], v[150:153], v[226:229], v[110:113]
	v_mfma_f32_16x16x32_bf16 v[106:109], v[158:161], v[226:229], v[106:109]
	v_mfma_f32_16x16x32_bf16 v[102:105], v[150:153], v[234:237], v[102:105]
	v_mfma_f32_16x16x32_bf16 v[98:101], v[158:161], v[234:237], v[98:101]
	v_mfma_f32_16x16x32_bf16 v[94:97], v[176:179], v[198:201], v[94:97]
	v_mfma_f32_16x16x32_bf16 v[90:93], v[184:187], v[198:201], v[90:93]
	v_mfma_f32_16x16x32_bf16 v[86:89], v[176:179], v[214:217], v[86:89]
	v_mfma_f32_16x16x32_bf16 v[82:85], v[184:187], v[214:217], v[82:85]
	v_mfma_f32_16x16x32_bf16 v[78:81], v[176:179], v[222:225], v[78:81]
	v_mfma_f32_16x16x32_bf16 v[74:77], v[184:187], v[222:225], v[74:77]
	v_mfma_f32_16x16x32_bf16 v[70:73], v[176:179], v[230:233], v[70:73]
	v_mfma_f32_16x16x32_bf16 v[66:69], v[184:187], v[230:233], v[66:69]
	v_mfma_f32_16x16x32_bf16 v[94:97], v[180:183], v[202:205], v[94:97]
	v_mfma_f32_16x16x32_bf16 v[90:93], v[194:197], v[202:205], v[90:93]
	v_mfma_f32_16x16x32_bf16 v[86:89], v[180:183], v[218:221], v[86:89]
	v_mfma_f32_16x16x32_bf16 v[82:85], v[194:197], v[218:221], v[82:85]
	v_mfma_f32_16x16x32_bf16 v[78:81], v[180:183], v[226:229], v[78:81]
	v_mfma_f32_16x16x32_bf16 v[74:77], v[194:197], v[226:229], v[74:77]
	v_mfma_f32_16x16x32_bf16 v[70:73], v[180:183], v[234:237], v[70:73]
	v_mfma_f32_16x16x32_bf16 v[66:69], v[194:197], v[234:237], v[66:69]
	s_barrier
	s_add_i32 s2, s16, s20
	v_lshl_add_u64 v[144:145], v[144:145], 0, s[14:15]
	s_mov_b32 m0, s2
	ds_read_b128 v[198:201], v191 offset:49152
	ds_read_b128 v[202:205], v191 offset:50176
	ds_read_b128 v[214:217], v191 offset:51200
	ds_read_b128 v[218:221], v191 offset:52224
	ds_read_b128 v[222:225], v191 offset:53248
	ds_read_b128 v[226:229], v191 offset:54272
	ds_read_b128 v[230:233], v191 offset:55296
	ds_read_b128 v[234:237], v191 offset:56320
	global_load_lds_dwordx4 v[144:145], off
	s_add_i32 m0, s2, 0x2000
	s_mov_b64 s[2:3], 0x40080
	v_lshl_add_u64 v[144:145], v[166:167], 0, s[14:15]
	v_lshl_add_u64 v[136:137], v[136:137], 0, s[2:3]
	s_add_i32 s2, s73, s20
	global_load_lds_dwordx4 v[144:145], off
	v_lshl_add_u64 v[144:145], v[136:137], 0, v[164:165]
	s_mov_b32 m0, s2
	v_lshl_add_u64 v[136:137], v[136:137], 0, v[174:175]
	global_load_lds_dwordx4 v[144:145], off
	s_add_i32 m0, s2, 0x2000
	s_nop 0
	global_load_lds_dwordx4 v[136:137], off
	v_lshl_add_u64 v[136:137], v[238:239], 0, s[14:15]
	s_mov_b32 m0, s91
	s_nop 0
	global_load_lds_dwordx4 v[136:137], off
	v_lshl_add_u64 v[136:137], v[240:241], 0, s[14:15]
	s_mov_b32 m0, s92
	s_nop 0
	global_load_lds_dwordx4 v[136:137], off
	s_waitcnt vmcnt(8)
	s_waitcnt lgkmcnt(0)
	s_barrier
	s_waitcnt lgkmcnt(0)
	v_mfma_f32_16x16x32_bf16 v[62:65], v[140:143], v[198:201], v[62:65]
	v_mfma_f32_16x16x32_bf16 v[58:61], v[154:157], v[198:201], v[58:61]
	v_mfma_f32_16x16x32_bf16 v[54:57], v[140:143], v[214:217], v[54:57]
	v_mfma_f32_16x16x32_bf16 v[50:53], v[154:157], v[214:217], v[50:53]
	v_mfma_f32_16x16x32_bf16 v[46:49], v[140:143], v[222:225], v[46:49]
	v_mfma_f32_16x16x32_bf16 v[42:45], v[154:157], v[222:225], v[42:45]
	v_mfma_f32_16x16x32_bf16 v[38:41], v[140:143], v[230:233], v[38:41]
	v_mfma_f32_16x16x32_bf16 v[34:37], v[154:157], v[230:233], v[34:37]
	v_mfma_f32_16x16x32_bf16 v[62:65], v[150:153], v[202:205], v[62:65]
	v_mfma_f32_16x16x32_bf16 v[58:61], v[158:161], v[202:205], v[58:61]
	v_mfma_f32_16x16x32_bf16 v[54:57], v[150:153], v[218:221], v[54:57]
	v_mfma_f32_16x16x32_bf16 v[50:53], v[158:161], v[218:221], v[50:53]
	v_mfma_f32_16x16x32_bf16 v[46:49], v[150:153], v[226:229], v[46:49]
	v_mfma_f32_16x16x32_bf16 v[42:45], v[158:161], v[226:229], v[42:45]
	v_mfma_f32_16x16x32_bf16 v[38:41], v[150:153], v[234:237], v[38:41]
	v_mfma_f32_16x16x32_bf16 v[34:37], v[158:161], v[234:237], v[34:37]
	v_mfma_f32_16x16x32_bf16 v[30:33], v[176:179], v[198:201], v[30:33]
	v_mfma_f32_16x16x32_bf16 v[26:29], v[184:187], v[198:201], v[26:29]
	v_mfma_f32_16x16x32_bf16 v[22:25], v[176:179], v[214:217], v[22:25]
	v_mfma_f32_16x16x32_bf16 v[18:21], v[184:187], v[214:217], v[18:21]
	v_mfma_f32_16x16x32_bf16 v[14:17], v[176:179], v[222:225], v[14:17]
	v_mfma_f32_16x16x32_bf16 v[10:13], v[184:187], v[222:225], v[10:13]
	v_mfma_f32_16x16x32_bf16 v[6:9], v[176:179], v[230:233], v[6:9]
	v_mfma_f32_16x16x32_bf16 v[2:5], v[184:187], v[230:233], v[2:5]
	v_mfma_f32_16x16x32_bf16 v[30:33], v[180:183], v[202:205], v[30:33]
	v_mfma_f32_16x16x32_bf16 v[26:29], v[194:197], v[202:205], v[26:29]
	v_mfma_f32_16x16x32_bf16 v[22:25], v[180:183], v[218:221], v[22:25]
	v_mfma_f32_16x16x32_bf16 v[18:21], v[194:197], v[218:221], v[18:21]
	v_mfma_f32_16x16x32_bf16 v[14:17], v[180:183], v[226:229], v[14:17]
	v_mfma_f32_16x16x32_bf16 v[10:13], v[194:197], v[226:229], v[10:13]
	v_mfma_f32_16x16x32_bf16 v[6:9], v[180:183], v[234:237], v[6:9]
	v_mfma_f32_16x16x32_bf16 v[2:5], v[194:197], v[234:237], v[2:5]
	s_barrier
	s_add_i32 s2, s34, 2
	s_cmp_gt_u32 s34, 13
	s_cbranch_scc1 .LBB0_334
	s_mov_b32 s34, s2
	s_branch .LBB0_320
.LBB0_334:
	s_setprio 0
	s_and_b64 vcc, exec, s[54:55]
	s_cbranch_vccz .LBB0_336
	s_barrier

.Ltb_res_skip:
	s_cmp_eq_u32 s6, 0
	s_cbranch_scc1 .Lprio_res_done
	s_setprio 1
.Lprio_res_done:
	s_add_i32 s49, s42, 2
	s_add_u32 s74, s40, 0x80
	s_addc_u32 s43, s41, 0
	s_add_i32 s76, 0, 0x10000
	s_cmp_eq_u32 s67, s42
	s_cselect_b32 s43, s3, s43
	s_cselect_b32 s42, s2, s74
	s_cselect_b32 s75, s47, s48
	s_cselect_b32 s74, s46, s34
	s_add_i32 s77, 0, 0x14000
	v_add_u32_e32 v142, s76, v196
	v_add_u32_e32 v166, s77, v196
	ds_read_b128 v[122:125], v142
	ds_read_b128 v[134:137], v142 offset:1024
	ds_read_b128 v[138:141], v142 offset:2048
	ds_read_b128 v[142:145], v142 offset:3072
	ds_read_b128 v[150:153], v166
	ds_read_b128 v[154:157], v166 offset:1024
	ds_read_b128 v[158:161], v166 offset:2048
	ds_read_b128 v[178:181], v166 offset:3072
	v_lshl_add_u64 v[166:167], s[40:41], 0, v[174:175]
	s_add_i32 m0, s54, 0xc000
	ds_read_b128 v[182:185], v200
	ds_read_b128 v[186:189], v200 offset:1024
	ds_read_b128 v[190:193], v200 offset:2048
	ds_read_b128 v[202:205], v200 offset:3072
	ds_read_b128 v[214:217], v200 offset:4096
	ds_read_b128 v[218:221], v200 offset:5120
	ds_read_b128 v[222:225], v200 offset:6144
	ds_read_b128 v[226:229], v200 offset:7168
	global_load_lds_dwordx4 v[166:167], off
	v_lshl_add_u64 v[166:167], s[40:41], 0, v[176:177]
	s_add_i32 m0, s54, 0xe000
	s_nop 0
	global_load_lds_dwordx4 v[166:167], off
	s_waitcnt vmcnt(8)
	s_waitcnt lgkmcnt(0)
	s_barrier
	s_waitcnt lgkmcnt(0)
	v_mfma_f32_16x16x32_bf16 v[130:133], v[122:125], v[182:185], 0
	v_mfma_f32_16x16x32_bf16 v[126:129], v[138:141], v[182:185], 0
	v_mfma_f32_16x16x32_bf16 v[110:113], v[122:125], v[190:193], 0
	v_mfma_f32_16x16x32_bf16 v[106:109], v[138:141], v[190:193], 0
	v_mfma_f32_16x16x32_bf16 v[94:97], v[122:125], v[214:217], 0
	v_mfma_f32_16x16x32_bf16 v[90:93], v[138:141], v[214:217], 0
	v_mfma_f32_16x16x32_bf16 v[78:81], v[122:125], v[222:225], 0
	v_mfma_f32_16x16x32_bf16 v[74:77], v[138:141], v[222:225], 0
	v_mfma_f32_16x16x32_bf16 v[130:133], v[134:137], v[186:189], v[130:133]
	v_mfma_f32_16x16x32_bf16 v[126:129], v[142:145], v[186:189], v[126:129]
	v_mfma_f32_16x16x32_bf16 v[110:113], v[134:137], v[202:205], v[110:113]
	v_mfma_f32_16x16x32_bf16 v[106:109], v[142:145], v[202:205], v[106:109]
	v_mfma_f32_16x16x32_bf16 v[94:97], v[134:137], v[218:221], v[94:97]
	v_mfma_f32_16x16x32_bf16 v[90:93], v[142:145], v[218:221], v[90:93]
	v_mfma_f32_16x16x32_bf16 v[78:81], v[134:137], v[226:229], v[78:81]
	v_mfma_f32_16x16x32_bf16 v[74:77], v[142:145], v[226:229], v[74:77]
	v_mfma_f32_16x16x32_bf16 v[118:121], v[150:153], v[182:185], 0
	v_mfma_f32_16x16x32_bf16 v[114:117], v[158:161], v[182:185], 0
	v_mfma_f32_16x16x32_bf16 v[102:105], v[150:153], v[190:193], 0
	v_mfma_f32_16x16x32_bf16 v[98:101], v[158:161], v[190:193], 0
	v_mfma_f32_16x16x32_bf16 v[86:89], v[150:153], v[214:217], 0
	v_mfma_f32_16x16x32_bf16 v[82:85], v[158:161], v[214:217], 0
	v_mfma_f32_16x16x32_bf16 v[70:73], v[150:153], v[222:225], 0
	v_mfma_f32_16x16x32_bf16 v[66:69], v[158:161], v[222:225], 0
	v_mfma_f32_16x16x32_bf16 v[118:121], v[154:157], v[186:189], v[118:121]
	v_mfma_f32_16x16x32_bf16 v[114:117], v[178:181], v[186:189], v[114:117]
	v_mfma_f32_16x16x32_bf16 v[102:105], v[154:157], v[202:205], v[102:105]
	v_mfma_f32_16x16x32_bf16 v[98:101], v[178:181], v[202:205], v[98:101]
	v_mfma_f32_16x16x32_bf16 v[86:89], v[154:157], v[218:221], v[86:89]
	v_mfma_f32_16x16x32_bf16 v[82:85], v[178:181], v[218:221], v[82:85]
	v_mfma_f32_16x16x32_bf16 v[70:73], v[154:157], v[226:229], v[70:73]
	v_mfma_f32_16x16x32_bf16 v[66:69], v[178:181], v[226:229], v[66:69]
	s_barrier
	s_add_i32 s76, s76, s51
	v_lshl_add_u64 v[166:167], s[74:75], 0, v[0:1]
	s_mov_b32 m0, s76
	ds_read_b128 v[182:185], v200 offset:16384
	ds_read_b128 v[186:189], v200 offset:17408
	ds_read_b128 v[190:193], v200 offset:18432
	ds_read_b128 v[202:205], v200 offset:19456
	ds_read_b128 v[214:217], v200 offset:20480
	ds_read_b128 v[218:221], v200 offset:21504
	ds_read_b128 v[222:225], v200 offset:22528
	ds_read_b128 v[226:229], v200 offset:23552
	global_load_lds_dwordx4 v[166:167], off
	s_add_i32 m0, s76, 0x2000
	v_lshl_add_u64 v[194:195], s[74:75], 0, v[172:173]
	s_add_u32 s74, s74, s16
	s_addc_u32 s75, s75, 0
	s_add_i32 s76, s77, s51
	global_load_lds_dwordx4 v[194:195], off
	v_lshl_add_u64 v[230:231], s[74:75], 0, v[0:1]
	s_mov_b32 m0, s76
	v_lshl_add_u64 v[232:233], s[74:75], 0, v[172:173]
	global_load_lds_dwordx4 v[230:231], off
	s_add_i32 m0, s76, 0x2000
	v_lshl_add_u64 v[234:235], s[42:43], 0, v[162:163]
	global_load_lds_dwordx4 v[232:233], off
	s_mov_b32 m0, s54
	v_lshl_add_u64 v[236:237], s[42:43], 0, v[164:165]
	global_load_lds_dwordx4 v[234:235], off
	s_mov_b32 m0, s55
	s_nop 0
	global_load_lds_dwordx4 v[236:237], off
	s_waitcnt vmcnt(8)
	s_waitcnt lgkmcnt(0)
	s_barrier
	s_waitcnt lgkmcnt(0)
	v_mfma_f32_16x16x32_bf16 v[62:65], v[122:125], v[182:185], 0
	v_mfma_f32_16x16x32_bf16 v[58:61], v[138:141], v[182:185], 0
	v_mfma_f32_16x16x32_bf16 v[46:49], v[122:125], v[190:193], 0
	v_mfma_f32_16x16x32_bf16 v[42:45], v[138:141], v[190:193], 0
	v_mfma_f32_16x16x32_bf16 v[30:33], v[122:125], v[214:217], 0
	v_mfma_f32_16x16x32_bf16 v[26:29], v[138:141], v[214:217], 0
	v_mfma_f32_16x16x32_bf16 v[14:17], v[122:125], v[222:225], 0
	v_mfma_f32_16x16x32_bf16 v[10:13], v[138:141], v[222:225], 0
	v_mfma_f32_16x16x32_bf16 v[62:65], v[134:137], v[186:189], v[62:65]
	v_mfma_f32_16x16x32_bf16 v[58:61], v[142:145], v[186:189], v[58:61]
	v_mfma_f32_16x16x32_bf16 v[46:49], v[134:137], v[202:205], v[46:49]
	v_mfma_f32_16x16x32_bf16 v[42:45], v[142:145], v[202:205], v[42:45]
	v_mfma_f32_16x16x32_bf16 v[30:33], v[134:137], v[218:221], v[30:33]
	v_mfma_f32_16x16x32_bf16 v[26:29], v[142:145], v[218:221], v[26:29]
	v_mfma_f32_16x16x32_bf16 v[14:17], v[134:137], v[226:229], v[14:17]
	v_mfma_f32_16x16x32_bf16 v[10:13], v[142:145], v[226:229], v[10:13]
	v_mfma_f32_16x16x32_bf16 v[54:57], v[150:153], v[182:185], 0
	v_mfma_f32_16x16x32_bf16 v[50:53], v[158:161], v[182:185], 0
	v_mfma_f32_16x16x32_bf16 v[38:41], v[150:153], v[190:193], 0
	v_mfma_f32_16x16x32_bf16 v[34:37], v[158:161], v[190:193], 0
	v_mfma_f32_16x16x32_bf16 v[22:25], v[150:153], v[214:217], 0
	v_mfma_f32_16x16x32_bf16 v[18:21], v[158:161], v[214:217], 0
	v_mfma_f32_16x16x32_bf16 v[6:9], v[150:153], v[222:225], 0
	v_mfma_f32_16x16x32_bf16 v[2:5], v[158:161], v[222:225], 0
	v_mfma_f32_16x16x32_bf16 v[54:57], v[154:157], v[186:189], v[54:57]
	v_mfma_f32_16x16x32_bf16 v[50:53], v[178:181], v[186:189], v[50:53]
	v_mfma_f32_16x16x32_bf16 v[38:41], v[154:157], v[202:205], v[38:41]
	v_mfma_f32_16x16x32_bf16 v[34:37], v[178:181], v[202:205], v[34:37]
	v_mfma_f32_16x16x32_bf16 v[22:25], v[154:157], v[218:221], v[22:25]
	v_mfma_f32_16x16x32_bf16 v[18:21], v[178:181], v[218:221], v[18:21]
	v_mfma_f32_16x16x32_bf16 v[6:9], v[154:157], v[226:229], v[6:9]
	v_mfma_f32_16x16x32_bf16 v[2:5], v[178:181], v[226:229], v[2:5]
	s_barrier
	s_add_i32 s74, 0, 0x18000
	s_add_i32 s75, 0, 0x1c000
	v_add_u32_e32 v142, s74, v196
	v_add_u32_e32 v178, s75, v196
	ds_read_b128 v[122:125], v142
	ds_read_b128 v[134:137], v142 offset:1024
	ds_read_b128 v[138:141], v142 offset:2048
	ds_read_b128 v[142:145], v142 offset:3072
	ds_read_b128 v[150:153], v178
	ds_read_b128 v[154:157], v178 offset:1024
	ds_read_b128 v[158:161], v178 offset:2048
	ds_read_b128 v[178:181], v178 offset:3072
	s_add_u32 s42, s42, s16
	s_addc_u32 s43, s43, 0
	s_mov_b32 m0, s58
	v_lshl_add_u64 v[238:239], s[42:43], 0, v[162:163]
	ds_read_b128 v[182:185], v200 offset:32768
	ds_read_b128 v[186:189], v200 offset:33792
	ds_read_b128 v[190:193], v200 offset:34816
	ds_read_b128 v[202:205], v200 offset:35840
	ds_read_b128 v[214:217], v200 offset:36864
	ds_read_b128 v[218:221], v200 offset:37888
	ds_read_b128 v[222:225], v200 offset:38912
	ds_read_b128 v[226:229], v200 offset:39936
	global_load_lds_dwordx4 v[238:239], off
	v_lshl_add_u64 v[238:239], s[42:43], 0, v[164:165]
	s_mov_b32 m0, s59
	s_nop 0
	global_load_lds_dwordx4 v[238:239], off
	s_waitcnt vmcnt(8)
	s_waitcnt lgkmcnt(0)
	s_barrier
	s_waitcnt lgkmcnt(0)
	v_mfma_f32_16x16x32_bf16 v[130:133], v[122:125], v[182:185], v[130:133]
	v_mfma_f32_16x16x32_bf16 v[126:129], v[138:141], v[182:185], v[126:129]
	v_mfma_f32_16x16x32_bf16 v[110:113], v[122:125], v[190:193], v[110:113]
	v_mfma_f32_16x16x32_bf16 v[106:109], v[138:141], v[190:193], v[106:109]
	v_mfma_f32_16x16x32_bf16 v[94:97], v[122:125], v[214:217], v[94:97]
	v_mfma_f32_16x16x32_bf16 v[90:93], v[138:141], v[214:217], v[90:93]
	v_mfma_f32_16x16x32_bf16 v[78:81], v[122:125], v[222:225], v[78:81]
	v_mfma_f32_16x16x32_bf16 v[74:77], v[138:141], v[222:225], v[74:77]
	v_mfma_f32_16x16x32_bf16 v[130:133], v[134:137], v[186:189], v[130:133]
	v_mfma_f32_16x16x32_bf16 v[126:129], v[142:145], v[186:189], v[126:129]
	v_mfma_f32_16x16x32_bf16 v[110:113], v[134:137], v[202:205], v[110:113]
	v_mfma_f32_16x16x32_bf16 v[106:109], v[142:145], v[202:205], v[106:109]
	v_mfma_f32_16x16x32_bf16 v[94:97], v[134:137], v[218:221], v[94:97]
	v_mfma_f32_16x16x32_bf16 v[90:93], v[142:145], v[218:221], v[90:93]
	v_mfma_f32_16x16x32_bf16 v[78:81], v[134:137], v[226:229], v[78:81]
	v_mfma_f32_16x16x32_bf16 v[74:77], v[142:145], v[226:229], v[74:77]
	v_mfma_f32_16x16x32_bf16 v[118:121], v[150:153], v[182:185], v[118:121]
	v_mfma_f32_16x16x32_bf16 v[114:117], v[158:161], v[182:185], v[114:117]
	v_mfma_f32_16x16x32_bf16 v[102:105], v[150:153], v[190:193], v[102:105]
	v_mfma_f32_16x16x32_bf16 v[98:101], v[158:161], v[190:193], v[98:101]
	v_mfma_f32_16x16x32_bf16 v[86:89], v[150:153], v[214:217], v[86:89]
	v_mfma_f32_16x16x32_bf16 v[82:85], v[158:161], v[214:217], v[82:85]
	v_mfma_f32_16x16x32_bf16 v[70:73], v[150:153], v[222:225], v[70:73]
	v_mfma_f32_16x16x32_bf16 v[66:69], v[158:161], v[222:225], v[66:69]
	v_mfma_f32_16x16x32_bf16 v[118:121], v[154:157], v[186:189], v[118:121]
	v_mfma_f32_16x16x32_bf16 v[114:117], v[178:181], v[186:189], v[114:117]
	v_mfma_f32_16x16x32_bf16 v[102:105], v[154:157], v[202:205], v[102:105]
	v_mfma_f32_16x16x32_bf16 v[98:101], v[178:181], v[202:205], v[98:101]
	v_mfma_f32_16x16x32_bf16 v[86:89], v[154:157], v[218:221], v[86:89]
	v_mfma_f32_16x16x32_bf16 v[82:85], v[178:181], v[218:221], v[82:85]
	v_mfma_f32_16x16x32_bf16 v[70:73], v[154:157], v[226:229], v[70:73]
	v_mfma_f32_16x16x32_bf16 v[66:69], v[178:181], v[226:229], v[66:69]
	s_barrier
	s_add_i32 s42, s74, s51
	v_lshl_add_u64 v[166:167], v[166:167], 0, s[14:15]
	s_mov_b32 m0, s42
	ds_read_b128 v[182:185], v200 offset:49152
	ds_read_b128 v[186:189], v200 offset:50176
	ds_read_b128 v[190:193], v200 offset:51200
	ds_read_b128 v[202:205], v200 offset:52224
	ds_read_b128 v[214:217], v200 offset:53248
	ds_read_b128 v[218:221], v200 offset:54272
	ds_read_b128 v[222:225], v200 offset:55296
	ds_read_b128 v[226:229], v200 offset:56320
	global_load_lds_dwordx4 v[166:167], off
	v_lshl_add_u64 v[166:167], v[194:195], 0, s[14:15]
	s_add_i32 m0, s42, 0x2000
	s_add_i32 s42, s75, s51
	global_load_lds_dwordx4 v[166:167], off
	v_lshl_add_u64 v[166:167], v[230:231], 0, s[14:15]
	s_mov_b32 m0, s42
	s_nop 0
	global_load_lds_dwordx4 v[166:167], off
	v_lshl_add_u64 v[166:167], v[232:233], 0, s[14:15]
	s_add_i32 m0, s42, 0x2000
	s_nop 0
	global_load_lds_dwordx4 v[166:167], off
	v_lshl_add_u64 v[166:167], v[234:235], 0, s[14:15]
	s_mov_b32 m0, s65
	s_nop 0
	global_load_lds_dwordx4 v[166:167], off
	v_lshl_add_u64 v[166:167], v[236:237], 0, s[14:15]
	s_mov_b32 m0, s66
	s_nop 0
	global_load_lds_dwordx4 v[166:167], off
	s_waitcnt vmcnt(8)
	s_waitcnt lgkmcnt(0)
	s_barrier
	s_waitcnt lgkmcnt(0)
	v_mfma_f32_16x16x32_bf16 v[62:65], v[122:125], v[182:185], v[62:65]
	v_mfma_f32_16x16x32_bf16 v[58:61], v[138:141], v[182:185], v[58:61]
	v_mfma_f32_16x16x32_bf16 v[46:49], v[122:125], v[190:193], v[46:49]
	v_mfma_f32_16x16x32_bf16 v[42:45], v[138:141], v[190:193], v[42:45]
	v_mfma_f32_16x16x32_bf16 v[30:33], v[122:125], v[214:217], v[30:33]
	v_mfma_f32_16x16x32_bf16 v[26:29], v[138:141], v[214:217], v[26:29]
	v_mfma_f32_16x16x32_bf16 v[14:17], v[122:125], v[222:225], v[14:17]
	v_mfma_f32_16x16x32_bf16 v[10:13], v[138:141], v[222:225], v[10:13]
	v_mfma_f32_16x16x32_bf16 v[62:65], v[134:137], v[186:189], v[62:65]
	v_mfma_f32_16x16x32_bf16 v[58:61], v[142:145], v[186:189], v[58:61]
	v_mfma_f32_16x16x32_bf16 v[46:49], v[134:137], v[202:205], v[46:49]
	v_mfma_f32_16x16x32_bf16 v[42:45], v[142:145], v[202:205], v[42:45]
	v_mfma_f32_16x16x32_bf16 v[30:33], v[134:137], v[218:221], v[30:33]
	v_mfma_f32_16x16x32_bf16 v[26:29], v[142:145], v[218:221], v[26:29]
	v_mfma_f32_16x16x32_bf16 v[14:17], v[134:137], v[226:229], v[14:17]
	v_mfma_f32_16x16x32_bf16 v[10:13], v[142:145], v[226:229], v[10:13]
	v_mfma_f32_16x16x32_bf16 v[54:57], v[150:153], v[182:185], v[54:57]
	v_mfma_f32_16x16x32_bf16 v[50:53], v[158:161], v[182:185], v[50:53]
	v_mfma_f32_16x16x32_bf16 v[38:41], v[150:153], v[190:193], v[38:41]
	v_mfma_f32_16x16x32_bf16 v[34:37], v[158:161], v[190:193], v[34:37]
	v_mfma_f32_16x16x32_bf16 v[22:25], v[150:153], v[214:217], v[22:25]
	v_mfma_f32_16x16x32_bf16 v[18:21], v[158:161], v[214:217], v[18:21]
	v_mfma_f32_16x16x32_bf16 v[6:9], v[150:153], v[222:225], v[6:9]
	v_mfma_f32_16x16x32_bf16 v[2:5], v[158:161], v[222:225], v[2:5]
	v_mfma_f32_16x16x32_bf16 v[54:57], v[154:157], v[186:189], v[54:57]
	v_mfma_f32_16x16x32_bf16 v[50:53], v[178:181], v[186:189], v[50:53]
	v_mfma_f32_16x16x32_bf16 v[38:41], v[154:157], v[202:205], v[38:41]
	v_mfma_f32_16x16x32_bf16 v[34:37], v[178:181], v[202:205], v[34:37]
	v_mfma_f32_16x16x32_bf16 v[22:25], v[154:157], v[218:221], v[22:25]
	v_mfma_f32_16x16x32_bf16 v[18:21], v[178:181], v[218:221], v[18:21]
	v_mfma_f32_16x16x32_bf16 v[6:9], v[154:157], v[226:229], v[6:9]
	v_mfma_f32_16x16x32_bf16 v[2:5], v[178:181], v[226:229], v[2:5]
	s_barrier
	s_add_u32 s40, s40, 0x100
	s_addc_u32 s41, s41, 0
	s_add_u32 s34, s34, 0x100
	s_addc_u32 s48, s48, 0
	s_cmp_ge_u32 s49, s64
	s_mov_b32 s42, s49
	s_cbranch_scc1 .Lpeel_k374_exit
.LBB0_374:
	s_add_i32 s49, s42, 2
	s_add_u32 s74, s40, 0x80
	s_addc_u32 s43, s41, 0
	s_add_i32 s76, 0, 0x10000
	s_cmp_eq_u32 s67, s42
	s_cselect_b32 s43, s3, s43
	s_cselect_b32 s42, s2, s74
	s_cselect_b32 s75, s47, s48
	s_cselect_b32 s74, s46, s34
	s_add_i32 s77, 0, 0x14000
	v_add_u32_e32 v142, s76, v196
	v_add_u32_e32 v166, s77, v196
	ds_read_b128 v[122:125], v142
	ds_read_b128 v[134:137], v142 offset:1024
	ds_read_b128 v[138:141], v142 offset:2048
	ds_read_b128 v[142:145], v142 offset:3072
	ds_read_b128 v[150:153], v166
	ds_read_b128 v[154:157], v166 offset:1024
	ds_read_b128 v[158:161], v166 offset:2048
	ds_read_b128 v[178:181], v166 offset:3072
	v_lshl_add_u64 v[166:167], s[40:41], 0, v[174:175]
	s_add_i32 m0, s54, 0xc000
	ds_read_b128 v[182:185], v200
	ds_read_b128 v[186:189], v200 offset:1024
	ds_read_b128 v[190:193], v200 offset:2048
	ds_read_b128 v[202:205], v200 offset:3072
	ds_read_b128 v[214:217], v200 offset:4096
	ds_read_b128 v[218:221], v200 offset:5120
	ds_read_b128 v[222:225], v200 offset:6144
	ds_read_b128 v[226:229], v200 offset:7168
	global_load_lds_dwordx4 v[166:167], off
	v_lshl_add_u64 v[166:167], s[40:41], 0, v[176:177]
	s_add_i32 m0, s54, 0xe000
	s_nop 0
	global_load_lds_dwordx4 v[166:167], off
	s_waitcnt vmcnt(8)
	s_waitcnt lgkmcnt(0)
	s_barrier
	s_waitcnt lgkmcnt(0)
	v_mfma_f32_16x16x32_bf16 v[130:133], v[122:125], v[182:185], v[130:133]
	v_mfma_f32_16x16x32_bf16 v[126:129], v[138:141], v[182:185], v[126:129]
	v_mfma_f32_16x16x32_bf16 v[110:113], v[122:125], v[190:193], v[110:113]
	v_mfma_f32_16x16x32_bf16 v[106:109], v[138:141], v[190:193], v[106:109]
	v_mfma_f32_16x16x32_bf16 v[94:97], v[122:125], v[214:217], v[94:97]
	v_mfma_f32_16x16x32_bf16 v[90:93], v[138:141], v[214:217], v[90:93]
	v_mfma_f32_16x16x32_bf16 v[78:81], v[122:125], v[222:225], v[78:81]
	v_mfma_f32_16x16x32_bf16 v[74:77], v[138:141], v[222:225], v[74:77]
	v_mfma_f32_16x16x32_bf16 v[130:133], v[134:137], v[186:189], v[130:133]
	v_mfma_f32_16x16x32_bf16 v[126:129], v[142:145], v[186:189], v[126:129]
	v_mfma_f32_16x16x32_bf16 v[110:113], v[134:137], v[202:205], v[110:113]
	v_mfma_f32_16x16x32_bf16 v[106:109], v[142:145], v[202:205], v[106:109]
	v_mfma_f32_16x16x32_bf16 v[94:97], v[134:137], v[218:221], v[94:97]
	v_mfma_f32_16x16x32_bf16 v[90:93], v[142:145], v[218:221], v[90:93]
	v_mfma_f32_16x16x32_bf16 v[78:81], v[134:137], v[226:229], v[78:81]
	v_mfma_f32_16x16x32_bf16 v[74:77], v[142:145], v[226:229], v[74:77]
	v_mfma_f32_16x16x32_bf16 v[118:121], v[150:153], v[182:185], v[118:121]
	v_mfma_f32_16x16x32_bf16 v[114:117], v[158:161], v[182:185], v[114:117]
	v_mfma_f32_16x16x32_bf16 v[102:105], v[150:153], v[190:193], v[102:105]
	v_mfma_f32_16x16x32_bf16 v[98:101], v[158:161], v[190:193], v[98:101]
	v_mfma_f32_16x16x32_bf16 v[86:89], v[150:153], v[214:217], v[86:89]
	v_mfma_f32_16x16x32_bf16 v[82:85], v[158:161], v[214:217], v[82:85]
	v_mfma_f32_16x16x32_bf16 v[70:73], v[150:153], v[222:225], v[70:73]
	v_mfma_f32_16x16x32_bf16 v[66:69], v[158:161], v[222:225], v[66:69]
	v_mfma_f32_16x16x32_bf16 v[118:121], v[154:157], v[186:189], v[118:121]
	v_mfma_f32_16x16x32_bf16 v[114:117], v[178:181], v[186:189], v[114:117]
	v_mfma_f32_16x16x32_bf16 v[102:105], v[154:157], v[202:205], v[102:105]
	v_mfma_f32_16x16x32_bf16 v[98:101], v[178:181], v[202:205], v[98:101]
	v_mfma_f32_16x16x32_bf16 v[86:89], v[154:157], v[218:221], v[86:89]
	v_mfma_f32_16x16x32_bf16 v[82:85], v[178:181], v[218:221], v[82:85]
	v_mfma_f32_16x16x32_bf16 v[70:73], v[154:157], v[226:229], v[70:73]
	v_mfma_f32_16x16x32_bf16 v[66:69], v[178:181], v[226:229], v[66:69]
	s_barrier
	s_add_i32 s76, s76, s51
	v_lshl_add_u64 v[166:167], s[74:75], 0, v[0:1]
	s_mov_b32 m0, s76
	ds_read_b128 v[182:185], v200 offset:16384
	ds_read_b128 v[186:189], v200 offset:17408
	ds_read_b128 v[190:193], v200 offset:18432
	ds_read_b128 v[202:205], v200 offset:19456
	ds_read_b128 v[214:217], v200 offset:20480
	ds_read_b128 v[218:221], v200 offset:21504
	ds_read_b128 v[222:225], v200 offset:22528
	ds_read_b128 v[226:229], v200 offset:23552
	global_load_lds_dwordx4 v[166:167], off
	s_add_i32 m0, s76, 0x2000
	v_lshl_add_u64 v[194:195], s[74:75], 0, v[172:173]
	s_add_u32 s74, s74, s16
	s_addc_u32 s75, s75, 0
	s_add_i32 s76, s77, s51
	global_load_lds_dwordx4 v[194:195], off
	v_lshl_add_u64 v[230:231], s[74:75], 0, v[0:1]
	s_mov_b32 m0, s76
	v_lshl_add_u64 v[232:233], s[74:75], 0, v[172:173]
	global_load_lds_dwordx4 v[230:231], off
	s_add_i32 m0, s76, 0x2000
	v_lshl_add_u64 v[234:235], s[42:43], 0, v[162:163]
	global_load_lds_dwordx4 v[232:233], off
	s_mov_b32 m0, s54
	v_lshl_add_u64 v[236:237], s[42:43], 0, v[164:165]
	global_load_lds_dwordx4 v[234:235], off
	s_mov_b32 m0, s55
	s_nop 0
	global_load_lds_dwordx4 v[236:237], off
	s_waitcnt vmcnt(8)
	s_waitcnt lgkmcnt(0)
	s_barrier
	s_waitcnt lgkmcnt(0)
	v_mfma_f32_16x16x32_bf16 v[62:65], v[122:125], v[182:185], v[62:65]
	v_mfma_f32_16x16x32_bf16 v[58:61], v[138:141], v[182:185], v[58:61]
	v_mfma_f32_16x16x32_bf16 v[46:49], v[122:125], v[190:193], v[46:49]
	v_mfma_f32_16x16x32_bf16 v[42:45], v[138:141], v[190:193], v[42:45]
	v_mfma_f32_16x16x32_bf16 v[30:33], v[122:125], v[214:217], v[30:33]
	v_mfma_f32_16x16x32_bf16 v[26:29], v[138:141], v[214:217], v[26:29]
	v_mfma_f32_16x16x32_bf16 v[14:17], v[122:125], v[222:225], v[14:17]
	v_mfma_f32_16x16x32_bf16 v[10:13], v[138:141], v[222:225], v[10:13]
	v_mfma_f32_16x16x32_bf16 v[62:65], v[134:137], v[186:189], v[62:65]
	v_mfma_f32_16x16x32_bf16 v[58:61], v[142:145], v[186:189], v[58:61]
	v_mfma_f32_16x16x32_bf16 v[46:49], v[134:137], v[202:205], v[46:49]
	v_mfma_f32_16x16x32_bf16 v[42:45], v[142:145], v[202:205], v[42:45]
	v_mfma_f32_16x16x32_bf16 v[30:33], v[134:137], v[218:221], v[30:33]
	v_mfma_f32_16x16x32_bf16 v[26:29], v[142:145], v[218:221], v[26:29]
	v_mfma_f32_16x16x32_bf16 v[14:17], v[134:137], v[226:229], v[14:17]
	v_mfma_f32_16x16x32_bf16 v[10:13], v[142:145], v[226:229], v[10:13]
	v_mfma_f32_16x16x32_bf16 v[54:57], v[150:153], v[182:185], v[54:57]
	v_mfma_f32_16x16x32_bf16 v[50:53], v[158:161], v[182:185], v[50:53]
	v_mfma_f32_16x16x32_bf16 v[38:41], v[150:153], v[190:193], v[38:41]
	v_mfma_f32_16x16x32_bf16 v[34:37], v[158:161], v[190:193], v[34:37]
	v_mfma_f32_16x16x32_bf16 v[22:25], v[150:153], v[214:217], v[22:25]
	v_mfma_f32_16x16x32_bf16 v[18:21], v[158:161], v[214:217], v[18:21]
	v_mfma_f32_16x16x32_bf16 v[6:9], v[150:153], v[222:225], v[6:9]
	v_mfma_f32_16x16x32_bf16 v[2:5], v[158:161], v[222:225], v[2:5]
	v_mfma_f32_16x16x32_bf16 v[54:57], v[154:157], v[186:189], v[54:57]
	v_mfma_f32_16x16x32_bf16 v[50:53], v[178:181], v[186:189], v[50:53]
	v_mfma_f32_16x16x32_bf16 v[38:41], v[154:157], v[202:205], v[38:41]
	v_mfma_f32_16x16x32_bf16 v[34:37], v[178:181], v[202:205], v[34:37]
	v_mfma_f32_16x16x32_bf16 v[22:25], v[154:157], v[218:221], v[22:25]
	v_mfma_f32_16x16x32_bf16 v[18:21], v[178:181], v[218:221], v[18:21]
	v_mfma_f32_16x16x32_bf16 v[6:9], v[154:157], v[226:229], v[6:9]
	v_mfma_f32_16x16x32_bf16 v[2:5], v[178:181], v[226:229], v[2:5]
	s_barrier
	s_add_i32 s74, 0, 0x18000
	s_add_i32 s75, 0, 0x1c000
	v_add_u32_e32 v142, s74, v196
	v_add_u32_e32 v178, s75, v196
	ds_read_b128 v[122:125], v142
	ds_read_b128 v[134:137], v142 offset:1024
	ds_read_b128 v[138:141], v142 offset:2048
	ds_read_b128 v[142:145], v142 offset:3072
	ds_read_b128 v[150:153], v178
	ds_read_b128 v[154:157], v178 offset:1024
	ds_read_b128 v[158:161], v178 offset:2048
	ds_read_b128 v[178:181], v178 offset:3072
	s_add_u32 s42, s42, s16
	s_addc_u32 s43, s43, 0
	s_mov_b32 m0, s58
	v_lshl_add_u64 v[238:239], s[42:43], 0, v[162:163]
	ds_read_b128 v[182:185], v200 offset:32768
	ds_read_b128 v[186:189], v200 offset:33792
	ds_read_b128 v[190:193], v200 offset:34816
	ds_read_b128 v[202:205], v200 offset:35840
	ds_read_b128 v[214:217], v200 offset:36864
	ds_read_b128 v[218:221], v200 offset:37888
	ds_read_b128 v[222:225], v200 offset:38912
	ds_read_b128 v[226:229], v200 offset:39936
	global_load_lds_dwordx4 v[238:239], off
	v_lshl_add_u64 v[238:239], s[42:43], 0, v[164:165]
	s_mov_b32 m0, s59
	s_nop 0
	global_load_lds_dwordx4 v[238:239], off
	s_waitcnt vmcnt(8)
	s_waitcnt lgkmcnt(0)
	s_barrier
	s_waitcnt lgkmcnt(0)
	v_mfma_f32_16x16x32_bf16 v[130:133], v[122:125], v[182:185], v[130:133]
	v_mfma_f32_16x16x32_bf16 v[126:129], v[138:141], v[182:185], v[126:129]
	v_mfma_f32_16x16x32_bf16 v[110:113], v[122:125], v[190:193], v[110:113]
	v_mfma_f32_16x16x32_bf16 v[106:109], v[138:141], v[190:193], v[106:109]
	v_mfma_f32_16x16x32_bf16 v[94:97], v[122:125], v[214:217], v[94:97]
	v_mfma_f32_16x16x32_bf16 v[90:93], v[138:141], v[214:217], v[90:93]
	v_mfma_f32_16x16x32_bf16 v[78:81], v[122:125], v[222:225], v[78:81]
	v_mfma_f32_16x16x32_bf16 v[74:77], v[138:141], v[222:225], v[74:77]
	v_mfma_f32_16x16x32_bf16 v[130:133], v[134:137], v[186:189], v[130:133]
	v_mfma_f32_16x16x32_bf16 v[126:129], v[142:145], v[186:189], v[126:129]
	v_mfma_f32_16x16x32_bf16 v[110:113], v[134:137], v[202:205], v[110:113]
	v_mfma_f32_16x16x32_bf16 v[106:109], v[142:145], v[202:205], v[106:109]
	v_mfma_f32_16x16x32_bf16 v[94:97], v[134:137], v[218:221], v[94:97]
	v_mfma_f32_16x16x32_bf16 v[90:93], v[142:145], v[218:221], v[90:93]
	v_mfma_f32_16x16x32_bf16 v[78:81], v[134:137], v[226:229], v[78:81]
	v_mfma_f32_16x16x32_bf16 v[74:77], v[142:145], v[226:229], v[74:77]
	v_mfma_f32_16x16x32_bf16 v[118:121], v[150:153], v[182:185], v[118:121]
	v_mfma_f32_16x16x32_bf16 v[114:117], v[158:161], v[182:185], v[114:117]
	v_mfma_f32_16x16x32_bf16 v[102:105], v[150:153], v[190:193], v[102:105]
	v_mfma_f32_16x16x32_bf16 v[98:101], v[158:161], v[190:193], v[98:101]
	v_mfma_f32_16x16x32_bf16 v[86:89], v[150:153], v[214:217], v[86:89]
	v_mfma_f32_16x16x32_bf16 v[82:85], v[158:161], v[214:217], v[82:85]
	v_mfma_f32_16x16x32_bf16 v[70:73], v[150:153], v[222:225], v[70:73]
	v_mfma_f32_16x16x32_bf16 v[66:69], v[158:161], v[222:225], v[66:69]
	v_mfma_f32_16x16x32_bf16 v[118:121], v[154:157], v[186:189], v[118:121]
	v_mfma_f32_16x16x32_bf16 v[114:117], v[178:181], v[186:189], v[114:117]
	v_mfma_f32_16x16x32_bf16 v[102:105], v[154:157], v[202:205], v[102:105]
	v_mfma_f32_16x16x32_bf16 v[98:101], v[178:181], v[202:205], v[98:101]
	v_mfma_f32_16x16x32_bf16 v[86:89], v[154:157], v[218:221], v[86:89]
	v_mfma_f32_16x16x32_bf16 v[82:85], v[178:181], v[218:221], v[82:85]
	v_mfma_f32_16x16x32_bf16 v[70:73], v[154:157], v[226:229], v[70:73]
	v_mfma_f32_16x16x32_bf16 v[66:69], v[178:181], v[226:229], v[66:69]
	s_barrier
	s_add_i32 s42, s74, s51
	v_lshl_add_u64 v[166:167], v[166:167], 0, s[14:15]
	s_mov_b32 m0, s42
	ds_read_b128 v[182:185], v200 offset:49152
	ds_read_b128 v[186:189], v200 offset:50176
	ds_read_b128 v[190:193], v200 offset:51200
	ds_read_b128 v[202:205], v200 offset:52224
	ds_read_b128 v[214:217], v200 offset:53248
	ds_read_b128 v[218:221], v200 offset:54272
	ds_read_b128 v[222:225], v200 offset:55296
	ds_read_b128 v[226:229], v200 offset:56320
	global_load_lds_dwordx4 v[166:167], off
	v_lshl_add_u64 v[166:167], v[194:195], 0, s[14:15]
	s_add_i32 m0, s42, 0x2000
	s_add_i32 s42, s75, s51
	global_load_lds_dwordx4 v[166:167], off
	v_lshl_add_u64 v[166:167], v[230:231], 0, s[14:15]
	s_mov_b32 m0, s42
	s_nop 0
	global_load_lds_dwordx4 v[166:167], off
	v_lshl_add_u64 v[166:167], v[232:233], 0, s[14:15]
	s_add_i32 m0, s42, 0x2000
	s_nop 0
	global_load_lds_dwordx4 v[166:167], off
	v_lshl_add_u64 v[166:167], v[234:235], 0, s[14:15]
	s_mov_b32 m0, s65
	s_nop 0
	global_load_lds_dwordx4 v[166:167], off
	v_lshl_add_u64 v[166:167], v[236:237], 0, s[14:15]
	s_mov_b32 m0, s66
	s_nop 0
	global_load_lds_dwordx4 v[166:167], off
	s_waitcnt vmcnt(8)
	s_waitcnt lgkmcnt(0)
	s_barrier
	s_waitcnt lgkmcnt(0)
	v_mfma_f32_16x16x32_bf16 v[62:65], v[122:125], v[182:185], v[62:65]
	v_mfma_f32_16x16x32_bf16 v[58:61], v[138:141], v[182:185], v[58:61]
	v_mfma_f32_16x16x32_bf16 v[46:49], v[122:125], v[190:193], v[46:49]
	v_mfma_f32_16x16x32_bf16 v[42:45], v[138:141], v[190:193], v[42:45]
	v_mfma_f32_16x16x32_bf16 v[30:33], v[122:125], v[214:217], v[30:33]
	v_mfma_f32_16x16x32_bf16 v[26:29], v[138:141], v[214:217], v[26:29]
	v_mfma_f32_16x16x32_bf16 v[14:17], v[122:125], v[222:225], v[14:17]
	v_mfma_f32_16x16x32_bf16 v[10:13], v[138:141], v[222:225], v[10:13]
	v_mfma_f32_16x16x32_bf16 v[62:65], v[134:137], v[186:189], v[62:65]
	v_mfma_f32_16x16x32_bf16 v[58:61], v[142:145], v[186:189], v[58:61]
	v_mfma_f32_16x16x32_bf16 v[46:49], v[134:137], v[202:205], v[46:49]
	v_mfma_f32_16x16x32_bf16 v[42:45], v[142:145], v[202:205], v[42:45]
	v_mfma_f32_16x16x32_bf16 v[30:33], v[134:137], v[218:221], v[30:33]
	v_mfma_f32_16x16x32_bf16 v[26:29], v[142:145], v[218:221], v[26:29]
	v_mfma_f32_16x16x32_bf16 v[14:17], v[134:137], v[226:229], v[14:17]
	v_mfma_f32_16x16x32_bf16 v[10:13], v[142:145], v[226:229], v[10:13]
	v_mfma_f32_16x16x32_bf16 v[54:57], v[150:153], v[182:185], v[54:57]
	v_mfma_f32_16x16x32_bf16 v[50:53], v[158:161], v[182:185], v[50:53]
	v_mfma_f32_16x16x32_bf16 v[38:41], v[150:153], v[190:193], v[38:41]
	v_mfma_f32_16x16x32_bf16 v[34:37], v[158:161], v[190:193], v[34:37]
	v_mfma_f32_16x16x32_bf16 v[22:25], v[150:153], v[214:217], v[22:25]
	v_mfma_f32_16x16x32_bf16 v[18:21], v[158:161], v[214:217], v[18:21]
	v_mfma_f32_16x16x32_bf16 v[6:9], v[150:153], v[222:225], v[6:9]
	v_mfma_f32_16x16x32_bf16 v[2:5], v[158:161], v[222:225], v[2:5]
	v_mfma_f32_16x16x32_bf16 v[54:57], v[154:157], v[186:189], v[54:57]
	v_mfma_f32_16x16x32_bf16 v[50:53], v[178:181], v[186:189], v[50:53]
	v_mfma_f32_16x16x32_bf16 v[38:41], v[154:157], v[202:205], v[38:41]
	v_mfma_f32_16x16x32_bf16 v[34:37], v[178:181], v[202:205], v[34:37]
	v_mfma_f32_16x16x32_bf16 v[22:25], v[154:157], v[218:221], v[22:25]
	v_mfma_f32_16x16x32_bf16 v[18:21], v[178:181], v[218:221], v[18:21]
	v_mfma_f32_16x16x32_bf16 v[6:9], v[154:157], v[226:229], v[6:9]
	v_mfma_f32_16x16x32_bf16 v[2:5], v[178:181], v[226:229], v[2:5]
	s_barrier
	s_add_u32 s40, s40, 0x100
	s_addc_u32 s41, s41, 0
	s_add_u32 s34, s34, 0x100
	s_addc_u32 s48, s48, 0
	s_cmp_ge_u32 s49, s64
	s_mov_b32 s42, s49
	s_cbranch_scc0 .LBB0_374
.Lpeel_k374_exit:
	s_setprio 0
	s_and_b64 vcc, exec, s[22:23]
	s_cbranch_vccz .LBB0_377
	s_barrier

.Lprio_sw_done:
	s_add_u32 s46, s44, 0xfffc0080
	s_addc_u32 s47, s45, -1
	s_add_i32 s51, 0, 0x10000
	s_cmp_eq_u32 s50, 12
	s_cselect_b32 s49, s16, s47
	s_cselect_b32 s48, s29, s46
	v_add_u32_e32 v0, s51, v198
	s_cselect_b32 s47, s23, s43
	s_cselect_b32 s46, s31, s34
	s_add_i32 s65, 0, 0x14000
	ds_read_b128 v[50:53], v0
	ds_read_b128 v[54:57], v0 offset:1024
	ds_read_b128 v[66:69], v0 offset:2048
	ds_read_b128 v[70:73], v0 offset:3072
	v_add_u32_e32 v0, s65, v198
	ds_read_b128 v[174:177], v0
	ds_read_b128 v[178:181], v0 offset:1024
	ds_read_b128 v[182:185], v0 offset:2048
	ds_read_b128 v[186:189], v0 offset:3072
	v_lshl_add_u64 v[166:167], s[44:45], 0, v[164:165]
	s_add_i32 m0, s52, 0xc000
	ds_read_b128 v[190:193], v203
	ds_read_b128 v[194:197], v203 offset:1024
	ds_read_b128 v[214:217], v203 offset:2048
	ds_read_b128 v[218:221], v203 offset:3072
	ds_read_b128 v[222:225], v203 offset:4096
	ds_read_b128 v[226:229], v203 offset:5120
	ds_read_b128 v[230:233], v203 offset:6144
	ds_read_b128 v[234:237], v203 offset:7168
	global_load_lds_dwordx4 v[166:167], off
	v_lshl_add_u64 v[166:167], s[44:45], 0, v[172:173]
	s_add_i32 m0, s52, 0xe000
	s_nop 0
	global_load_lds_dwordx4 v[166:167], off
	s_waitcnt vmcnt(8)
	s_waitcnt lgkmcnt(0)
	s_barrier
	s_waitcnt lgkmcnt(0)
	v_mfma_f32_16x16x32_bf16 v[142:145], v[50:53], v[190:193], 0
	v_mfma_f32_16x16x32_bf16 v[138:141], v[66:69], v[190:193], 0
	v_mfma_f32_16x16x32_bf16 v[126:129], v[50:53], v[214:217], 0
	v_mfma_f32_16x16x32_bf16 v[122:125], v[66:69], v[214:217], 0
	v_mfma_f32_16x16x32_bf16 v[110:113], v[50:53], v[222:225], 0
	v_mfma_f32_16x16x32_bf16 v[106:109], v[66:69], v[222:225], 0
	v_mfma_f32_16x16x32_bf16 v[94:97], v[50:53], v[230:233], 0
	v_mfma_f32_16x16x32_bf16 v[90:93], v[66:69], v[230:233], 0
	v_mfma_f32_16x16x32_bf16 v[142:145], v[54:57], v[194:197], v[142:145]
	v_mfma_f32_16x16x32_bf16 v[138:141], v[70:73], v[194:197], v[138:141]
	v_mfma_f32_16x16x32_bf16 v[126:129], v[54:57], v[218:221], v[126:129]
	v_mfma_f32_16x16x32_bf16 v[122:125], v[70:73], v[218:221], v[122:125]
	v_mfma_f32_16x16x32_bf16 v[110:113], v[54:57], v[226:229], v[110:113]
	v_mfma_f32_16x16x32_bf16 v[106:109], v[70:73], v[226:229], v[106:109]
	v_mfma_f32_16x16x32_bf16 v[94:97], v[54:57], v[234:237], v[94:97]
	v_mfma_f32_16x16x32_bf16 v[90:93], v[70:73], v[234:237], v[90:93]
	v_mfma_f32_16x16x32_bf16 v[134:137], v[174:177], v[190:193], 0
	v_mfma_f32_16x16x32_bf16 v[130:133], v[182:185], v[190:193], 0
	v_mfma_f32_16x16x32_bf16 v[118:121], v[174:177], v[214:217], 0
	v_mfma_f32_16x16x32_bf16 v[114:117], v[182:185], v[214:217], 0
	v_mfma_f32_16x16x32_bf16 v[102:105], v[174:177], v[222:225], 0
	v_mfma_f32_16x16x32_bf16 v[98:101], v[182:185], v[222:225], 0
	v_mfma_f32_16x16x32_bf16 v[86:89], v[174:177], v[230:233], 0
	v_mfma_f32_16x16x32_bf16 v[82:85], v[182:185], v[230:233], 0
	v_mfma_f32_16x16x32_bf16 v[134:137], v[178:181], v[194:197], v[134:137]
	v_mfma_f32_16x16x32_bf16 v[130:133], v[186:189], v[194:197], v[130:133]
	v_mfma_f32_16x16x32_bf16 v[118:121], v[178:181], v[218:221], v[118:121]
	v_mfma_f32_16x16x32_bf16 v[114:117], v[186:189], v[218:221], v[114:117]
	v_mfma_f32_16x16x32_bf16 v[102:105], v[178:181], v[226:229], v[102:105]
	v_mfma_f32_16x16x32_bf16 v[98:101], v[186:189], v[226:229], v[98:101]
	v_mfma_f32_16x16x32_bf16 v[86:89], v[178:181], v[234:237], v[86:89]
	v_mfma_f32_16x16x32_bf16 v[82:85], v[186:189], v[234:237], v[82:85]
	s_barrier
	s_add_i32 s51, s51, s12
	v_lshl_add_u64 v[166:167], s[46:47], 0, v[152:153]
	s_mov_b32 m0, s51
	ds_read_b128 v[190:193], v203 offset:16384
	ds_read_b128 v[194:197], v203 offset:17408
	ds_read_b128 v[214:217], v203 offset:18432
	ds_read_b128 v[218:221], v203 offset:19456
	ds_read_b128 v[222:225], v203 offset:20480
	ds_read_b128 v[226:229], v203 offset:21504
	ds_read_b128 v[230:233], v203 offset:22528
	ds_read_b128 v[234:237], v203 offset:23552
	global_load_lds_dwordx4 v[166:167], off
	s_add_i32 m0, s51, 0x2000
	s_add_u32 s66, s46, 0x40000
	v_lshl_add_u64 v[204:205], s[46:47], 0, v[156:157]
	s_addc_u32 s67, s47, 0
	s_add_i32 s51, s65, s12
	global_load_lds_dwordx4 v[204:205], off
	v_lshl_add_u64 v[238:239], s[66:67], 0, v[152:153]
	s_mov_b32 m0, s51
	v_lshl_add_u64 v[240:241], s[48:49], 0, v[154:155]
	global_load_lds_dwordx4 v[238:239], off
	v_lshl_add_u64 v[238:239], s[66:67], 0, v[156:157]
	s_add_i32 m0, s51, 0x2000
	s_nop 0
	global_load_lds_dwordx4 v[238:239], off
	v_lshl_add_u64 v[238:239], s[48:49], 0, v[150:151]
	s_mov_b32 m0, s52
	s_nop 0
	global_load_lds_dwordx4 v[238:239], off
	s_mov_b32 m0, s53
	s_nop 0
	global_load_lds_dwordx4 v[240:241], off
	s_waitcnt vmcnt(8)
	s_waitcnt lgkmcnt(0)
	s_barrier
	s_waitcnt lgkmcnt(0)
	v_mfma_f32_16x16x32_bf16 v[78:81], v[50:53], v[190:193], 0
	v_mfma_f32_16x16x32_bf16 v[74:77], v[66:69], v[190:193], 0
	v_mfma_f32_16x16x32_bf16 v[46:49], v[50:53], v[214:217], 0
	v_mfma_f32_16x16x32_bf16 v[42:45], v[66:69], v[214:217], 0
	v_mfma_f32_16x16x32_bf16 v[30:33], v[50:53], v[222:225], 0
	v_mfma_f32_16x16x32_bf16 v[26:29], v[66:69], v[222:225], 0
	v_mfma_f32_16x16x32_bf16 v[14:17], v[50:53], v[230:233], 0
	v_mfma_f32_16x16x32_bf16 v[10:13], v[66:69], v[230:233], 0
	v_mfma_f32_16x16x32_bf16 v[78:81], v[54:57], v[194:197], v[78:81]
	v_mfma_f32_16x16x32_bf16 v[74:77], v[70:73], v[194:197], v[74:77]
	v_mfma_f32_16x16x32_bf16 v[46:49], v[54:57], v[218:221], v[46:49]
	v_mfma_f32_16x16x32_bf16 v[42:45], v[70:73], v[218:221], v[42:45]
	v_mfma_f32_16x16x32_bf16 v[30:33], v[54:57], v[226:229], v[30:33]
	v_mfma_f32_16x16x32_bf16 v[26:29], v[70:73], v[226:229], v[26:29]
	v_mfma_f32_16x16x32_bf16 v[14:17], v[54:57], v[234:237], v[14:17]
	v_mfma_f32_16x16x32_bf16 v[10:13], v[70:73], v[234:237], v[10:13]
	v_mfma_f32_16x16x32_bf16 v[38:41], v[174:177], v[214:217], 0
	v_mfma_f32_16x16x32_bf16 v[34:37], v[182:185], v[214:217], 0
	v_mfma_f32_16x16x32_bf16 v[22:25], v[174:177], v[222:225], 0
	v_mfma_f32_16x16x32_bf16 v[18:21], v[182:185], v[222:225], 0
	v_mfma_f32_16x16x32_bf16 v[6:9], v[174:177], v[230:233], 0
	v_mfma_f32_16x16x32_bf16 v[2:5], v[182:185], v[230:233], 0
	v_mfma_f32_16x16x32_bf16 v[50:53], v[174:177], v[190:193], 0
	v_mfma_f32_16x16x32_bf16 v[54:57], v[182:185], v[190:193], 0
	v_mfma_f32_16x16x32_bf16 v[38:41], v[178:181], v[218:221], v[38:41]
	v_mfma_f32_16x16x32_bf16 v[34:37], v[186:189], v[218:221], v[34:37]
	v_mfma_f32_16x16x32_bf16 v[22:25], v[178:181], v[226:229], v[22:25]
	v_mfma_f32_16x16x32_bf16 v[18:21], v[186:189], v[226:229], v[18:21]
	v_mfma_f32_16x16x32_bf16 v[6:9], v[178:181], v[234:237], v[6:9]
	v_mfma_f32_16x16x32_bf16 v[2:5], v[186:189], v[234:237], v[2:5]
	v_mfma_f32_16x16x32_bf16 v[50:53], v[178:181], v[194:197], v[50:53]
	v_mfma_f32_16x16x32_bf16 v[54:57], v[186:189], v[194:197], v[54:57]
	s_barrier
	s_add_i32 s51, 0, 0x18000
	v_add_u32_e32 v0, s51, v198
	s_add_i32 s65, 0, 0x1c000
	ds_read_b128 v[58:61], v0
	ds_read_b128 v[62:65], v0 offset:1024
	ds_read_b128 v[66:69], v0 offset:2048
	ds_read_b128 v[70:73], v0 offset:3072
	v_add_u32_e32 v0, s65, v198
	ds_read_b128 v[174:177], v0
	ds_read_b128 v[178:181], v0 offset:1024
	ds_read_b128 v[182:185], v0 offset:2048
	ds_read_b128 v[186:189], v0 offset:3072
	s_add_u32 s48, s48, 0x40000
	s_addc_u32 s49, s49, 0
	s_mov_b32 m0, s54
	v_lshl_add_u64 v[242:243], s[48:49], 0, v[150:151]
	ds_read_b128 v[190:193], v203 offset:32768
	ds_read_b128 v[194:197], v203 offset:33792
	ds_read_b128 v[214:217], v203 offset:34816
	ds_read_b128 v[218:221], v203 offset:35840
	ds_read_b128 v[222:225], v203 offset:36864
	ds_read_b128 v[226:229], v203 offset:37888
	ds_read_b128 v[230:233], v203 offset:38912
	ds_read_b128 v[234:237], v203 offset:39936
	global_load_lds_dwordx4 v[242:243], off
	v_lshl_add_u64 v[242:243], s[48:49], 0, v[154:155]
	s_mov_b32 m0, s55
	s_nop 0
	global_load_lds_dwordx4 v[242:243], off
	s_waitcnt vmcnt(8)
	s_waitcnt lgkmcnt(0)
	s_barrier
	s_waitcnt lgkmcnt(0)
	v_mfma_f32_16x16x32_bf16 v[142:145], v[58:61], v[190:193], v[142:145]
	v_mfma_f32_16x16x32_bf16 v[138:141], v[66:69], v[190:193], v[138:141]
	v_mfma_f32_16x16x32_bf16 v[126:129], v[58:61], v[214:217], v[126:129]
	v_mfma_f32_16x16x32_bf16 v[122:125], v[66:69], v[214:217], v[122:125]
	v_mfma_f32_16x16x32_bf16 v[110:113], v[58:61], v[222:225], v[110:113]
	v_mfma_f32_16x16x32_bf16 v[106:109], v[66:69], v[222:225], v[106:109]
	v_mfma_f32_16x16x32_bf16 v[94:97], v[58:61], v[230:233], v[94:97]
	v_mfma_f32_16x16x32_bf16 v[90:93], v[66:69], v[230:233], v[90:93]
	v_mfma_f32_16x16x32_bf16 v[142:145], v[62:65], v[194:197], v[142:145]
	v_mfma_f32_16x16x32_bf16 v[138:141], v[70:73], v[194:197], v[138:141]
	v_mfma_f32_16x16x32_bf16 v[126:129], v[62:65], v[218:221], v[126:129]
	v_mfma_f32_16x16x32_bf16 v[122:125], v[70:73], v[218:221], v[122:125]
	v_mfma_f32_16x16x32_bf16 v[110:113], v[62:65], v[226:229], v[110:113]
	v_mfma_f32_16x16x32_bf16 v[106:109], v[70:73], v[226:229], v[106:109]
	v_mfma_f32_16x16x32_bf16 v[94:97], v[62:65], v[234:237], v[94:97]
	v_mfma_f32_16x16x32_bf16 v[90:93], v[70:73], v[234:237], v[90:93]
	v_mfma_f32_16x16x32_bf16 v[134:137], v[174:177], v[190:193], v[134:137]
	v_mfma_f32_16x16x32_bf16 v[130:133], v[182:185], v[190:193], v[130:133]
	v_mfma_f32_16x16x32_bf16 v[118:121], v[174:177], v[214:217], v[118:121]
	v_mfma_f32_16x16x32_bf16 v[114:117], v[182:185], v[214:217], v[114:117]
	v_mfma_f32_16x16x32_bf16 v[102:105], v[174:177], v[222:225], v[102:105]
	v_mfma_f32_16x16x32_bf16 v[98:101], v[182:185], v[222:225], v[98:101]
	v_mfma_f32_16x16x32_bf16 v[86:89], v[174:177], v[230:233], v[86:89]
	v_mfma_f32_16x16x32_bf16 v[82:85], v[182:185], v[230:233], v[82:85]
	v_mfma_f32_16x16x32_bf16 v[134:137], v[178:181], v[194:197], v[134:137]
	v_mfma_f32_16x16x32_bf16 v[130:133], v[186:189], v[194:197], v[130:133]
	v_mfma_f32_16x16x32_bf16 v[118:121], v[178:181], v[218:221], v[118:121]
	v_mfma_f32_16x16x32_bf16 v[114:117], v[186:189], v[218:221], v[114:117]
	v_mfma_f32_16x16x32_bf16 v[102:105], v[178:181], v[226:229], v[102:105]
	v_mfma_f32_16x16x32_bf16 v[98:101], v[186:189], v[226:229], v[98:101]
	v_mfma_f32_16x16x32_bf16 v[86:89], v[178:181], v[234:237], v[86:89]
	v_mfma_f32_16x16x32_bf16 v[82:85], v[186:189], v[234:237], v[82:85]
	s_barrier
	s_add_i32 s48, s51, s12
	v_lshl_add_u64 v[166:167], v[166:167], 0, s[14:15]
	s_mov_b32 m0, s48
	ds_read_b128 v[190:193], v203 offset:49152
	ds_read_b128 v[194:197], v203 offset:50176
	ds_read_b128 v[214:217], v203 offset:51200
	ds_read_b128 v[218:221], v203 offset:52224
	ds_read_b128 v[222:225], v203 offset:53248
	ds_read_b128 v[226:229], v203 offset:54272
	ds_read_b128 v[230:233], v203 offset:55296
	ds_read_b128 v[234:237], v203 offset:56320
	global_load_lds_dwordx4 v[166:167], off
	s_add_i32 m0, s48, 0x2000
	s_add_u32 s46, s46, 0x40080
	v_lshl_add_u64 v[166:167], v[204:205], 0, s[14:15]
	s_addc_u32 s47, s47, 0
	s_add_i32 s48, s65, s12
	global_load_lds_dwordx4 v[166:167], off
	v_lshl_add_u64 v[166:167], s[46:47], 0, v[152:153]
	s_mov_b32 m0, s48
	s_nop 0
	global_load_lds_dwordx4 v[166:167], off
	v_lshl_add_u64 v[166:167], s[46:47], 0, v[156:157]
	s_add_i32 m0, s48, 0x2000
	s_nop 0
	global_load_lds_dwordx4 v[166:167], off
	v_lshl_add_u64 v[166:167], v[238:239], 0, s[14:15]
	s_mov_b32 m0, s59
	s_nop 0
	global_load_lds_dwordx4 v[166:167], off
	v_lshl_add_u64 v[166:167], v[240:241], 0, s[14:15]
	s_mov_b32 m0, s60
	s_nop 0
	global_load_lds_dwordx4 v[166:167], off
	s_waitcnt vmcnt(8)
	s_waitcnt lgkmcnt(0)
	s_barrier
	s_waitcnt lgkmcnt(0)
	v_mfma_f32_16x16x32_bf16 v[78:81], v[58:61], v[190:193], v[78:81]
	v_mfma_f32_16x16x32_bf16 v[74:77], v[66:69], v[190:193], v[74:77]
	v_mfma_f32_16x16x32_bf16 v[46:49], v[58:61], v[214:217], v[46:49]
	v_mfma_f32_16x16x32_bf16 v[42:45], v[66:69], v[214:217], v[42:45]
	v_mfma_f32_16x16x32_bf16 v[30:33], v[58:61], v[222:225], v[30:33]
	v_mfma_f32_16x16x32_bf16 v[26:29], v[66:69], v[222:225], v[26:29]
	v_mfma_f32_16x16x32_bf16 v[14:17], v[58:61], v[230:233], v[14:17]
	v_mfma_f32_16x16x32_bf16 v[10:13], v[66:69], v[230:233], v[10:13]
	v_mfma_f32_16x16x32_bf16 v[78:81], v[62:65], v[194:197], v[78:81]
	v_mfma_f32_16x16x32_bf16 v[74:77], v[70:73], v[194:197], v[74:77]
	v_mfma_f32_16x16x32_bf16 v[46:49], v[62:65], v[218:221], v[46:49]
	v_mfma_f32_16x16x32_bf16 v[42:45], v[70:73], v[218:221], v[42:45]
	v_mfma_f32_16x16x32_bf16 v[30:33], v[62:65], v[226:229], v[30:33]
	v_mfma_f32_16x16x32_bf16 v[26:29], v[70:73], v[226:229], v[26:29]
	v_mfma_f32_16x16x32_bf16 v[14:17], v[62:65], v[234:237], v[14:17]
	v_mfma_f32_16x16x32_bf16 v[10:13], v[70:73], v[234:237], v[10:13]
	v_mfma_f32_16x16x32_bf16 v[50:53], v[174:177], v[190:193], v[50:53]
	v_mfma_f32_16x16x32_bf16 v[62:65], v[178:181], v[194:197], v[50:53]
	v_mfma_f32_16x16x32_bf16 v[50:53], v[182:185], v[190:193], v[54:57]
	v_mfma_f32_16x16x32_bf16 v[38:41], v[174:177], v[214:217], v[38:41]
	v_mfma_f32_16x16x32_bf16 v[34:37], v[182:185], v[214:217], v[34:37]
	v_mfma_f32_16x16x32_bf16 v[22:25], v[174:177], v[222:225], v[22:25]
	v_mfma_f32_16x16x32_bf16 v[18:21], v[182:185], v[222:225], v[18:21]
	v_mfma_f32_16x16x32_bf16 v[6:9], v[174:177], v[230:233], v[6:9]
	v_mfma_f32_16x16x32_bf16 v[2:5], v[182:185], v[230:233], v[2:5]
	v_mfma_f32_16x16x32_bf16 v[58:61], v[186:189], v[194:197], v[50:53]
	v_mfma_f32_16x16x32_bf16 v[38:41], v[178:181], v[218:221], v[38:41]
	v_mfma_f32_16x16x32_bf16 v[34:37], v[186:189], v[218:221], v[34:37]
	v_mfma_f32_16x16x32_bf16 v[22:25], v[178:181], v[226:229], v[22:25]
	v_mfma_f32_16x16x32_bf16 v[18:21], v[186:189], v[226:229], v[18:21]
	v_mfma_f32_16x16x32_bf16 v[6:9], v[178:181], v[234:237], v[6:9]
	v_mfma_f32_16x16x32_bf16 v[2:5], v[186:189], v[234:237], v[2:5]
	s_barrier
	s_add_i32 s50, s50, 2
	s_add_u32 s44, s44, 0x100
	s_addc_u32 s45, s45, 0
	s_add_u32 s34, s34, 0x100
	s_addc_u32 s43, s43, 0
	s_cmp_gt_u32 s50, 13
	s_cbranch_scc1 .Lpeel_k511_exit
.LBB0_511:
	s_add_u32 s46, s44, 0xfffc0080
	s_addc_u32 s47, s45, -1
	s_add_i32 s51, 0, 0x10000
	s_cmp_eq_u32 s50, 12
	s_cselect_b32 s49, s16, s47
	s_cselect_b32 s48, s29, s46
	v_add_u32_e32 v0, s51, v198
	s_cselect_b32 s47, s23, s43
	s_cselect_b32 s46, s31, s34
	s_add_i32 s65, 0, 0x14000
	ds_read_b128 v[50:53], v0
	ds_read_b128 v[54:57], v0 offset:1024
	ds_read_b128 v[66:69], v0 offset:2048
	ds_read_b128 v[70:73], v0 offset:3072
	v_add_u32_e32 v0, s65, v198
	ds_read_b128 v[174:177], v0
	ds_read_b128 v[178:181], v0 offset:1024
	ds_read_b128 v[182:185], v0 offset:2048
	ds_read_b128 v[186:189], v0 offset:3072
	v_lshl_add_u64 v[166:167], s[44:45], 0, v[164:165]
	s_add_i32 m0, s52, 0xc000
	ds_read_b128 v[190:193], v203
	ds_read_b128 v[194:197], v203 offset:1024
	ds_read_b128 v[214:217], v203 offset:2048
	ds_read_b128 v[218:221], v203 offset:3072
	ds_read_b128 v[222:225], v203 offset:4096
	ds_read_b128 v[226:229], v203 offset:5120
	ds_read_b128 v[230:233], v203 offset:6144
	ds_read_b128 v[234:237], v203 offset:7168
	global_load_lds_dwordx4 v[166:167], off
	v_lshl_add_u64 v[166:167], s[44:45], 0, v[172:173]
	s_add_i32 m0, s52, 0xe000
	s_nop 0
	global_load_lds_dwordx4 v[166:167], off
	s_waitcnt vmcnt(8)
	s_waitcnt lgkmcnt(0)
	s_barrier
	s_waitcnt lgkmcnt(0)
	v_mfma_f32_16x16x32_bf16 v[142:145], v[50:53], v[190:193], v[142:145]
	v_mfma_f32_16x16x32_bf16 v[138:141], v[66:69], v[190:193], v[138:141]
	v_mfma_f32_16x16x32_bf16 v[126:129], v[50:53], v[214:217], v[126:129]
	v_mfma_f32_16x16x32_bf16 v[122:125], v[66:69], v[214:217], v[122:125]
	v_mfma_f32_16x16x32_bf16 v[110:113], v[50:53], v[222:225], v[110:113]
	v_mfma_f32_16x16x32_bf16 v[106:109], v[66:69], v[222:225], v[106:109]
	v_mfma_f32_16x16x32_bf16 v[94:97], v[50:53], v[230:233], v[94:97]
	v_mfma_f32_16x16x32_bf16 v[90:93], v[66:69], v[230:233], v[90:93]
	v_mfma_f32_16x16x32_bf16 v[142:145], v[54:57], v[194:197], v[142:145]
	v_mfma_f32_16x16x32_bf16 v[138:141], v[70:73], v[194:197], v[138:141]
	v_mfma_f32_16x16x32_bf16 v[126:129], v[54:57], v[218:221], v[126:129]
	v_mfma_f32_16x16x32_bf16 v[122:125], v[70:73], v[218:221], v[122:125]
	v_mfma_f32_16x16x32_bf16 v[110:113], v[54:57], v[226:229], v[110:113]
	v_mfma_f32_16x16x32_bf16 v[106:109], v[70:73], v[226:229], v[106:109]
	v_mfma_f32_16x16x32_bf16 v[94:97], v[54:57], v[234:237], v[94:97]
	v_mfma_f32_16x16x32_bf16 v[90:93], v[70:73], v[234:237], v[90:93]
	v_mfma_f32_16x16x32_bf16 v[134:137], v[174:177], v[190:193], v[134:137]
	v_mfma_f32_16x16x32_bf16 v[130:133], v[182:185], v[190:193], v[130:133]
	v_mfma_f32_16x16x32_bf16 v[118:121], v[174:177], v[214:217], v[118:121]
	v_mfma_f32_16x16x32_bf16 v[114:117], v[182:185], v[214:217], v[114:117]
	v_mfma_f32_16x16x32_bf16 v[102:105], v[174:177], v[222:225], v[102:105]
	v_mfma_f32_16x16x32_bf16 v[98:101], v[182:185], v[222:225], v[98:101]
	v_mfma_f32_16x16x32_bf16 v[86:89], v[174:177], v[230:233], v[86:89]
	v_mfma_f32_16x16x32_bf16 v[82:85], v[182:185], v[230:233], v[82:85]
	v_mfma_f32_16x16x32_bf16 v[134:137], v[178:181], v[194:197], v[134:137]
	v_mfma_f32_16x16x32_bf16 v[130:133], v[186:189], v[194:197], v[130:133]
	v_mfma_f32_16x16x32_bf16 v[118:121], v[178:181], v[218:221], v[118:121]
	v_mfma_f32_16x16x32_bf16 v[114:117], v[186:189], v[218:221], v[114:117]
	v_mfma_f32_16x16x32_bf16 v[102:105], v[178:181], v[226:229], v[102:105]
	v_mfma_f32_16x16x32_bf16 v[98:101], v[186:189], v[226:229], v[98:101]
	v_mfma_f32_16x16x32_bf16 v[86:89], v[178:181], v[234:237], v[86:89]
	v_mfma_f32_16x16x32_bf16 v[82:85], v[186:189], v[234:237], v[82:85]
	s_barrier
	s_add_i32 s51, s51, s12
	v_lshl_add_u64 v[166:167], s[46:47], 0, v[152:153]
	s_mov_b32 m0, s51
	ds_read_b128 v[190:193], v203 offset:16384
	ds_read_b128 v[194:197], v203 offset:17408
	ds_read_b128 v[214:217], v203 offset:18432
	ds_read_b128 v[218:221], v203 offset:19456
	ds_read_b128 v[222:225], v203 offset:20480
	ds_read_b128 v[226:229], v203 offset:21504
	ds_read_b128 v[230:233], v203 offset:22528
	ds_read_b128 v[234:237], v203 offset:23552
	global_load_lds_dwordx4 v[166:167], off
	s_add_i32 m0, s51, 0x2000
	s_add_u32 s66, s46, 0x40000
	v_lshl_add_u64 v[204:205], s[46:47], 0, v[156:157]
	s_addc_u32 s67, s47, 0
	s_add_i32 s51, s65, s12
	global_load_lds_dwordx4 v[204:205], off
	v_lshl_add_u64 v[238:239], s[66:67], 0, v[152:153]
	s_mov_b32 m0, s51
	v_lshl_add_u64 v[240:241], s[48:49], 0, v[154:155]
	global_load_lds_dwordx4 v[238:239], off
	v_lshl_add_u64 v[238:239], s[66:67], 0, v[156:157]
	s_add_i32 m0, s51, 0x2000
	s_nop 0
	global_load_lds_dwordx4 v[238:239], off
	v_lshl_add_u64 v[238:239], s[48:49], 0, v[150:151]
	s_mov_b32 m0, s52
	s_nop 0
	global_load_lds_dwordx4 v[238:239], off
	s_mov_b32 m0, s53
	s_nop 0
	global_load_lds_dwordx4 v[240:241], off
	s_waitcnt vmcnt(8)
	s_waitcnt lgkmcnt(0)
	s_barrier
	s_waitcnt lgkmcnt(0)
	v_mfma_f32_16x16x32_bf16 v[78:81], v[50:53], v[190:193], v[78:81]
	v_mfma_f32_16x16x32_bf16 v[74:77], v[66:69], v[190:193], v[74:77]
	v_mfma_f32_16x16x32_bf16 v[46:49], v[50:53], v[214:217], v[46:49]
	v_mfma_f32_16x16x32_bf16 v[42:45], v[66:69], v[214:217], v[42:45]
	v_mfma_f32_16x16x32_bf16 v[30:33], v[50:53], v[222:225], v[30:33]
	v_mfma_f32_16x16x32_bf16 v[26:29], v[66:69], v[222:225], v[26:29]
	v_mfma_f32_16x16x32_bf16 v[14:17], v[50:53], v[230:233], v[14:17]
	v_mfma_f32_16x16x32_bf16 v[10:13], v[66:69], v[230:233], v[10:13]
	v_mfma_f32_16x16x32_bf16 v[78:81], v[54:57], v[194:197], v[78:81]
	v_mfma_f32_16x16x32_bf16 v[74:77], v[70:73], v[194:197], v[74:77]
	v_mfma_f32_16x16x32_bf16 v[46:49], v[54:57], v[218:221], v[46:49]
	v_mfma_f32_16x16x32_bf16 v[42:45], v[70:73], v[218:221], v[42:45]
	v_mfma_f32_16x16x32_bf16 v[30:33], v[54:57], v[226:229], v[30:33]
	v_mfma_f32_16x16x32_bf16 v[26:29], v[70:73], v[226:229], v[26:29]
	v_mfma_f32_16x16x32_bf16 v[14:17], v[54:57], v[234:237], v[14:17]
	v_mfma_f32_16x16x32_bf16 v[10:13], v[70:73], v[234:237], v[10:13]
	v_mfma_f32_16x16x32_bf16 v[38:41], v[174:177], v[214:217], v[38:41]
	v_mfma_f32_16x16x32_bf16 v[34:37], v[182:185], v[214:217], v[34:37]
	v_mfma_f32_16x16x32_bf16 v[22:25], v[174:177], v[222:225], v[22:25]
	v_mfma_f32_16x16x32_bf16 v[18:21], v[182:185], v[222:225], v[18:21]
	v_mfma_f32_16x16x32_bf16 v[6:9], v[174:177], v[230:233], v[6:9]
	v_mfma_f32_16x16x32_bf16 v[2:5], v[182:185], v[230:233], v[2:5]
	v_mfma_f32_16x16x32_bf16 v[50:53], v[174:177], v[190:193], v[62:65]
	v_mfma_f32_16x16x32_bf16 v[54:57], v[182:185], v[190:193], v[58:61]
	v_mfma_f32_16x16x32_bf16 v[38:41], v[178:181], v[218:221], v[38:41]
	v_mfma_f32_16x16x32_bf16 v[34:37], v[186:189], v[218:221], v[34:37]
	v_mfma_f32_16x16x32_bf16 v[22:25], v[178:181], v[226:229], v[22:25]
	v_mfma_f32_16x16x32_bf16 v[18:21], v[186:189], v[226:229], v[18:21]
	v_mfma_f32_16x16x32_bf16 v[6:9], v[178:181], v[234:237], v[6:9]
	v_mfma_f32_16x16x32_bf16 v[2:5], v[186:189], v[234:237], v[2:5]
	v_mfma_f32_16x16x32_bf16 v[50:53], v[178:181], v[194:197], v[50:53]
	v_mfma_f32_16x16x32_bf16 v[54:57], v[186:189], v[194:197], v[54:57]
	s_barrier
	s_add_i32 s51, 0, 0x18000
	v_add_u32_e32 v0, s51, v198
	s_add_i32 s65, 0, 0x1c000
	ds_read_b128 v[58:61], v0
	ds_read_b128 v[62:65], v0 offset:1024
	ds_read_b128 v[66:69], v0 offset:2048
	ds_read_b128 v[70:73], v0 offset:3072
	v_add_u32_e32 v0, s65, v198
	ds_read_b128 v[174:177], v0
	ds_read_b128 v[178:181], v0 offset:1024
	ds_read_b128 v[182:185], v0 offset:2048
	ds_read_b128 v[186:189], v0 offset:3072
	s_add_u32 s48, s48, 0x40000
	s_addc_u32 s49, s49, 0
	s_mov_b32 m0, s54
	v_lshl_add_u64 v[242:243], s[48:49], 0, v[150:151]
	ds_read_b128 v[190:193], v203 offset:32768
	ds_read_b128 v[194:197], v203 offset:33792
	ds_read_b128 v[214:217], v203 offset:34816
	ds_read_b128 v[218:221], v203 offset:35840
	ds_read_b128 v[222:225], v203 offset:36864
	ds_read_b128 v[226:229], v203 offset:37888
	ds_read_b128 v[230:233], v203 offset:38912
	ds_read_b128 v[234:237], v203 offset:39936
	global_load_lds_dwordx4 v[242:243], off
	v_lshl_add_u64 v[242:243], s[48:49], 0, v[154:155]
	s_mov_b32 m0, s55
	s_nop 0
	global_load_lds_dwordx4 v[242:243], off
	s_waitcnt vmcnt(8)
	s_waitcnt lgkmcnt(0)
	s_barrier
	s_waitcnt lgkmcnt(0)
	v_mfma_f32_16x16x32_bf16 v[142:145], v[58:61], v[190:193], v[142:145]
	v_mfma_f32_16x16x32_bf16 v[138:141], v[66:69], v[190:193], v[138:141]
	v_mfma_f32_16x16x32_bf16 v[126:129], v[58:61], v[214:217], v[126:129]
	v_mfma_f32_16x16x32_bf16 v[122:125], v[66:69], v[214:217], v[122:125]
	v_mfma_f32_16x16x32_bf16 v[110:113], v[58:61], v[222:225], v[110:113]
	v_mfma_f32_16x16x32_bf16 v[106:109], v[66:69], v[222:225], v[106:109]
	v_mfma_f32_16x16x32_bf16 v[94:97], v[58:61], v[230:233], v[94:97]
	v_mfma_f32_16x16x32_bf16 v[90:93], v[66:69], v[230:233], v[90:93]
	v_mfma_f32_16x16x32_bf16 v[142:145], v[62:65], v[194:197], v[142:145]
	v_mfma_f32_16x16x32_bf16 v[138:141], v[70:73], v[194:197], v[138:141]
	v_mfma_f32_16x16x32_bf16 v[126:129], v[62:65], v[218:221], v[126:129]
	v_mfma_f32_16x16x32_bf16 v[122:125], v[70:73], v[218:221], v[122:125]
	v_mfma_f32_16x16x32_bf16 v[110:113], v[62:65], v[226:229], v[110:113]
	v_mfma_f32_16x16x32_bf16 v[106:109], v[70:73], v[226:229], v[106:109]
	v_mfma_f32_16x16x32_bf16 v[94:97], v[62:65], v[234:237], v[94:97]
	v_mfma_f32_16x16x32_bf16 v[90:93], v[70:73], v[234:237], v[90:93]
	v_mfma_f32_16x16x32_bf16 v[134:137], v[174:177], v[190:193], v[134:137]
	v_mfma_f32_16x16x32_bf16 v[130:133], v[182:185], v[190:193], v[130:133]
	v_mfma_f32_16x16x32_bf16 v[118:121], v[174:177], v[214:217], v[118:121]
	v_mfma_f32_16x16x32_bf16 v[114:117], v[182:185], v[214:217], v[114:117]
	v_mfma_f32_16x16x32_bf16 v[102:105], v[174:177], v[222:225], v[102:105]
	v_mfma_f32_16x16x32_bf16 v[98:101], v[182:185], v[222:225], v[98:101]
	v_mfma_f32_16x16x32_bf16 v[86:89], v[174:177], v[230:233], v[86:89]
	v_mfma_f32_16x16x32_bf16 v[82:85], v[182:185], v[230:233], v[82:85]
	v_mfma_f32_16x16x32_bf16 v[134:137], v[178:181], v[194:197], v[134:137]
	v_mfma_f32_16x16x32_bf16 v[130:133], v[186:189], v[194:197], v[130:133]
	v_mfma_f32_16x16x32_bf16 v[118:121], v[178:181], v[218:221], v[118:121]
	v_mfma_f32_16x16x32_bf16 v[114:117], v[186:189], v[218:221], v[114:117]
	v_mfma_f32_16x16x32_bf16 v[102:105], v[178:181], v[226:229], v[102:105]
	v_mfma_f32_16x16x32_bf16 v[98:101], v[186:189], v[226:229], v[98:101]
	v_mfma_f32_16x16x32_bf16 v[86:89], v[178:181], v[234:237], v[86:89]
	v_mfma_f32_16x16x32_bf16 v[82:85], v[186:189], v[234:237], v[82:85]
	s_barrier
	s_add_i32 s48, s51, s12
	v_lshl_add_u64 v[166:167], v[166:167], 0, s[14:15]
	s_mov_b32 m0, s48
	ds_read_b128 v[190:193], v203 offset:49152
	ds_read_b128 v[194:197], v203 offset:50176
	ds_read_b128 v[214:217], v203 offset:51200
	ds_read_b128 v[218:221], v203 offset:52224
	ds_read_b128 v[222:225], v203 offset:53248
	ds_read_b128 v[226:229], v203 offset:54272
	ds_read_b128 v[230:233], v203 offset:55296
	ds_read_b128 v[234:237], v203 offset:56320
	global_load_lds_dwordx4 v[166:167], off
	s_add_i32 m0, s48, 0x2000
	s_add_u32 s46, s46, 0x40080
	v_lshl_add_u64 v[166:167], v[204:205], 0, s[14:15]
	s_addc_u32 s47, s47, 0
	s_add_i32 s48, s65, s12
	global_load_lds_dwordx4 v[166:167], off
	v_lshl_add_u64 v[166:167], s[46:47], 0, v[152:153]
	s_mov_b32 m0, s48
	s_nop 0
	global_load_lds_dwordx4 v[166:167], off
	v_lshl_add_u64 v[166:167], s[46:47], 0, v[156:157]
	s_add_i32 m0, s48, 0x2000
	s_nop 0
	global_load_lds_dwordx4 v[166:167], off
	v_lshl_add_u64 v[166:167], v[238:239], 0, s[14:15]
	s_mov_b32 m0, s59
	s_nop 0
	global_load_lds_dwordx4 v[166:167], off
	v_lshl_add_u64 v[166:167], v[240:241], 0, s[14:15]
	s_mov_b32 m0, s60
	s_nop 0
	global_load_lds_dwordx4 v[166:167], off
	s_waitcnt vmcnt(8)
	s_waitcnt lgkmcnt(0)
	s_barrier
	s_waitcnt lgkmcnt(0)
	v_mfma_f32_16x16x32_bf16 v[78:81], v[58:61], v[190:193], v[78:81]
	v_mfma_f32_16x16x32_bf16 v[74:77], v[66:69], v[190:193], v[74:77]
	v_mfma_f32_16x16x32_bf16 v[46:49], v[58:61], v[214:217], v[46:49]
	v_mfma_f32_16x16x32_bf16 v[42:45], v[66:69], v[214:217], v[42:45]
	v_mfma_f32_16x16x32_bf16 v[30:33], v[58:61], v[222:225], v[30:33]
	v_mfma_f32_16x16x32_bf16 v[26:29], v[66:69], v[222:225], v[26:29]
	v_mfma_f32_16x16x32_bf16 v[14:17], v[58:61], v[230:233], v[14:17]
	v_mfma_f32_16x16x32_bf16 v[10:13], v[66:69], v[230:233], v[10:13]
	v_mfma_f32_16x16x32_bf16 v[78:81], v[62:65], v[194:197], v[78:81]
	v_mfma_f32_16x16x32_bf16 v[74:77], v[70:73], v[194:197], v[74:77]
	v_mfma_f32_16x16x32_bf16 v[46:49], v[62:65], v[218:221], v[46:49]
	v_mfma_f32_16x16x32_bf16 v[42:45], v[70:73], v[218:221], v[42:45]
	v_mfma_f32_16x16x32_bf16 v[30:33], v[62:65], v[226:229], v[30:33]
	v_mfma_f32_16x16x32_bf16 v[26:29], v[70:73], v[226:229], v[26:29]
	v_mfma_f32_16x16x32_bf16 v[14:17], v[62:65], v[234:237], v[14:17]
	v_mfma_f32_16x16x32_bf16 v[10:13], v[70:73], v[234:237], v[10:13]
	v_mfma_f32_16x16x32_bf16 v[50:53], v[174:177], v[190:193], v[50:53]
	v_mfma_f32_16x16x32_bf16 v[62:65], v[178:181], v[194:197], v[50:53]
	v_mfma_f32_16x16x32_bf16 v[50:53], v[182:185], v[190:193], v[54:57]
	v_mfma_f32_16x16x32_bf16 v[38:41], v[174:177], v[214:217], v[38:41]
	v_mfma_f32_16x16x32_bf16 v[34:37], v[182:185], v[214:217], v[34:37]
	v_mfma_f32_16x16x32_bf16 v[22:25], v[174:177], v[222:225], v[22:25]
	v_mfma_f32_16x16x32_bf16 v[18:21], v[182:185], v[222:225], v[18:21]
	v_mfma_f32_16x16x32_bf16 v[6:9], v[174:177], v[230:233], v[6:9]
	v_mfma_f32_16x16x32_bf16 v[2:5], v[182:185], v[230:233], v[2:5]
	v_mfma_f32_16x16x32_bf16 v[58:61], v[186:189], v[194:197], v[50:53]
	v_mfma_f32_16x16x32_bf16 v[38:41], v[178:181], v[218:221], v[38:41]
	v_mfma_f32_16x16x32_bf16 v[34:37], v[186:189], v[218:221], v[34:37]
	v_mfma_f32_16x16x32_bf16 v[22:25], v[178:181], v[226:229], v[22:25]
	v_mfma_f32_16x16x32_bf16 v[18:21], v[186:189], v[226:229], v[18:21]
	v_mfma_f32_16x16x32_bf16 v[6:9], v[178:181], v[234:237], v[6:9]
	v_mfma_f32_16x16x32_bf16 v[2:5], v[186:189], v[234:237], v[2:5]
	s_barrier
	s_add_i32 s50, s50, 2
	s_add_u32 s44, s44, 0x100
	s_addc_u32 s45, s45, 0
	s_add_u32 s34, s34, 0x100
	s_addc_u32 s43, s43, 0
	s_cmp_gt_u32 s50, 13
	s_cbranch_scc0 .LBB0_511
.Lpeel_k511_exit:
	s_setprio 0
	s_and_b64 vcc, exec, s[8:9]
	s_cbranch_vccz .LBB0_514
	s_barrier

.Ltb_hg_skip:
	s_cmp_eq_u32 s4, 0
	s_cbranch_scc1 .Lprio_hg_done
	s_setprio 1
.Lprio_hg_done:
	s_add_u32 s39, s44, 0xfffc0080
	s_addc_u32 s43, s45, -1
	s_add_i32 s50, 0, 0x10000
	s_cmp_eq_u32 s34, 12
	s_cselect_b32 s49, s21, s43
	s_cselect_b32 s48, s23, s39
	s_cselect_b32 s47, s19, s29
	s_cselect_b32 s46, s26, s27
	s_add_i32 s39, 0, 0x14000
	v_add_u32_e32 v142, s50, v222
	v_add_u32_e32 v166, s39, v222
	ds_read_b128 v[130:133], v142
	ds_read_b128 v[134:137], v142 offset:1024
	ds_read_b128 v[138:141], v142 offset:2048
	ds_read_b128 v[142:145], v142 offset:3072
	s_waitcnt lgkmcnt(0)
	ds_read_b128 v[174:177], v166
	ds_read_b128 v[178:181], v166 offset:1024
	ds_read_b128 v[182:185], v166 offset:2048
	ds_read_b128 v[186:189], v166 offset:3072
	v_lshl_add_u64 v[244:245], s[44:45], 0, v[162:163]
	s_add_i32 m0, s55, 0xc000
	ds_read_b128 v[190:193], v157
	ds_read_b128 v[194:197], v157 offset:1024
	ds_read_b128 v[198:201], v157 offset:2048
	ds_read_b128 v[202:205], v157 offset:3072
	ds_read_b128 v[228:231], v157 offset:4096
	ds_read_b128 v[232:235], v157 offset:5120
	ds_read_b128 v[236:239], v157 offset:6144
	ds_read_b128 v[240:243], v157 offset:7168
	global_load_lds_dwordx4 v[244:245], off
	v_lshl_add_u64 v[244:245], s[44:45], 0, v[164:165]
	s_add_i32 m0, s55, 0xe000
	s_nop 0
	global_load_lds_dwordx4 v[244:245], off
	s_waitcnt vmcnt(8)
	s_waitcnt lgkmcnt(0)
	s_barrier
	s_waitcnt lgkmcnt(0)
	v_mfma_f32_16x16x32_bf16 v[126:129], v[130:133], v[190:193], 0
	v_mfma_f32_16x16x32_bf16 v[122:125], v[138:141], v[190:193], 0
	v_mfma_f32_16x16x32_bf16 v[110:113], v[130:133], v[198:201], 0
	v_mfma_f32_16x16x32_bf16 v[106:109], v[138:141], v[198:201], 0
	v_mfma_f32_16x16x32_bf16 v[94:97], v[130:133], v[228:231], 0
	v_mfma_f32_16x16x32_bf16 v[90:93], v[138:141], v[228:231], 0
	v_mfma_f32_16x16x32_bf16 v[78:81], v[130:133], v[236:239], 0
	v_mfma_f32_16x16x32_bf16 v[74:77], v[138:141], v[236:239], 0
	v_mfma_f32_16x16x32_bf16 v[126:129], v[134:137], v[194:197], v[126:129]
	v_mfma_f32_16x16x32_bf16 v[122:125], v[142:145], v[194:197], v[122:125]
	v_mfma_f32_16x16x32_bf16 v[110:113], v[134:137], v[202:205], v[110:113]
	v_mfma_f32_16x16x32_bf16 v[106:109], v[142:145], v[202:205], v[106:109]
	v_mfma_f32_16x16x32_bf16 v[94:97], v[134:137], v[232:235], v[94:97]
	v_mfma_f32_16x16x32_bf16 v[90:93], v[142:145], v[232:235], v[90:93]
	v_mfma_f32_16x16x32_bf16 v[78:81], v[134:137], v[240:243], v[78:81]
	v_mfma_f32_16x16x32_bf16 v[74:77], v[142:145], v[240:243], v[74:77]
	v_mfma_f32_16x16x32_bf16 v[118:121], v[174:177], v[190:193], 0
	v_mfma_f32_16x16x32_bf16 v[114:117], v[182:185], v[190:193], 0
	v_mfma_f32_16x16x32_bf16 v[102:105], v[174:177], v[198:201], 0
	v_mfma_f32_16x16x32_bf16 v[98:101], v[182:185], v[198:201], 0
	v_mfma_f32_16x16x32_bf16 v[86:89], v[174:177], v[228:231], 0
	v_mfma_f32_16x16x32_bf16 v[82:85], v[182:185], v[228:231], 0
	v_mfma_f32_16x16x32_bf16 v[70:73], v[174:177], v[236:239], 0
	v_mfma_f32_16x16x32_bf16 v[66:69], v[182:185], v[236:239], 0
	v_mfma_f32_16x16x32_bf16 v[118:121], v[178:181], v[194:197], v[118:121]
	v_mfma_f32_16x16x32_bf16 v[114:117], v[186:189], v[194:197], v[114:117]
	v_mfma_f32_16x16x32_bf16 v[102:105], v[178:181], v[202:205], v[102:105]
	v_mfma_f32_16x16x32_bf16 v[98:101], v[186:189], v[202:205], v[98:101]
	v_mfma_f32_16x16x32_bf16 v[86:89], v[178:181], v[232:235], v[86:89]
	v_mfma_f32_16x16x32_bf16 v[82:85], v[186:189], v[232:235], v[82:85]
	v_mfma_f32_16x16x32_bf16 v[70:73], v[178:181], v[240:243], v[70:73]
	v_mfma_f32_16x16x32_bf16 v[66:69], v[186:189], v[240:243], v[66:69]
	s_barrier
	s_add_i32 s43, s50, s13
	v_lshl_add_u64 v[244:245], s[46:47], 0, v[0:1]
	s_mov_b32 m0, s43
	ds_read_b128 v[190:193], v157 offset:16384
	ds_read_b128 v[194:197], v157 offset:17408
	ds_read_b128 v[198:201], v157 offset:18432
	ds_read_b128 v[202:205], v157 offset:19456
	ds_read_b128 v[228:231], v157 offset:20480
	ds_read_b128 v[232:235], v157 offset:21504
	ds_read_b128 v[236:239], v157 offset:22528
	ds_read_b128 v[240:243], v157 offset:23552
	global_load_lds_dwordx4 v[244:245], off
	s_add_i32 m0, s43, 0x2000
	s_add_u32 s50, s46, 0x40000
	v_lshl_add_u64 v[246:247], s[46:47], 0, v[154:155]
	s_addc_u32 s51, s47, 0
	s_add_i32 s39, s39, s13
	global_load_lds_dwordx4 v[246:247], off
	v_lshl_add_u64 v[248:249], s[50:51], 0, v[0:1]
	s_mov_b32 m0, s39
	v_lshl_add_u64 v[250:251], s[48:49], 0, v[152:153]
	global_load_lds_dwordx4 v[248:249], off
	v_lshl_add_u64 v[248:249], s[50:51], 0, v[154:155]
	s_add_i32 m0, s39, 0x2000
	s_nop 0
	global_load_lds_dwordx4 v[248:249], off
	v_lshl_add_u64 v[248:249], s[48:49], 0, v[150:151]
	s_mov_b32 m0, s55
	s_nop 0
	global_load_lds_dwordx4 v[248:249], off
	s_mov_b32 m0, s56
	s_nop 0
	global_load_lds_dwordx4 v[250:251], off
	s_waitcnt vmcnt(8)
	s_waitcnt lgkmcnt(0)
	s_barrier
	s_waitcnt lgkmcnt(0)
	v_mfma_f32_16x16x32_bf16 v[62:65], v[130:133], v[190:193], 0
	v_mfma_f32_16x16x32_bf16 v[58:61], v[138:141], v[190:193], 0
	v_mfma_f32_16x16x32_bf16 v[46:49], v[130:133], v[198:201], 0
	v_mfma_f32_16x16x32_bf16 v[42:45], v[138:141], v[198:201], 0
	v_mfma_f32_16x16x32_bf16 v[30:33], v[130:133], v[228:231], 0
	v_mfma_f32_16x16x32_bf16 v[26:29], v[138:141], v[228:231], 0
	v_mfma_f32_16x16x32_bf16 v[14:17], v[130:133], v[236:239], 0
	v_mfma_f32_16x16x32_bf16 v[10:13], v[138:141], v[236:239], 0
	v_mfma_f32_16x16x32_bf16 v[62:65], v[134:137], v[194:197], v[62:65]
	v_mfma_f32_16x16x32_bf16 v[58:61], v[142:145], v[194:197], v[58:61]
	v_mfma_f32_16x16x32_bf16 v[46:49], v[134:137], v[202:205], v[46:49]
	v_mfma_f32_16x16x32_bf16 v[42:45], v[142:145], v[202:205], v[42:45]
	v_mfma_f32_16x16x32_bf16 v[30:33], v[134:137], v[232:235], v[30:33]
	v_mfma_f32_16x16x32_bf16 v[26:29], v[142:145], v[232:235], v[26:29]
	v_mfma_f32_16x16x32_bf16 v[14:17], v[134:137], v[240:243], v[14:17]
	v_mfma_f32_16x16x32_bf16 v[10:13], v[142:145], v[240:243], v[10:13]
	v_mfma_f32_16x16x32_bf16 v[54:57], v[174:177], v[190:193], 0
	v_mfma_f32_16x16x32_bf16 v[50:53], v[182:185], v[190:193], 0
	v_mfma_f32_16x16x32_bf16 v[38:41], v[174:177], v[198:201], 0
	v_mfma_f32_16x16x32_bf16 v[34:37], v[182:185], v[198:201], 0
	v_mfma_f32_16x16x32_bf16 v[22:25], v[174:177], v[228:231], 0
	v_mfma_f32_16x16x32_bf16 v[18:21], v[182:185], v[228:231], 0
	v_mfma_f32_16x16x32_bf16 v[6:9], v[174:177], v[236:239], 0
	v_mfma_f32_16x16x32_bf16 v[2:5], v[182:185], v[236:239], 0
	v_mfma_f32_16x16x32_bf16 v[54:57], v[178:181], v[194:197], v[54:57]
	v_mfma_f32_16x16x32_bf16 v[50:53], v[186:189], v[194:197], v[50:53]
	v_mfma_f32_16x16x32_bf16 v[38:41], v[178:181], v[202:205], v[38:41]
	v_mfma_f32_16x16x32_bf16 v[34:37], v[186:189], v[202:205], v[34:37]
	v_mfma_f32_16x16x32_bf16 v[22:25], v[178:181], v[232:235], v[22:25]
	v_mfma_f32_16x16x32_bf16 v[18:21], v[186:189], v[232:235], v[18:21]
	v_mfma_f32_16x16x32_bf16 v[6:9], v[178:181], v[240:243], v[6:9]
	v_mfma_f32_16x16x32_bf16 v[2:5], v[186:189], v[240:243], v[2:5]
	s_barrier
	s_add_i32 s39, 0, 0x18000
	s_add_i32 s43, 0, 0x1c000
	v_add_u32_e32 v142, s39, v222
	v_add_u32_e32 v166, s43, v222
	ds_read_b128 v[130:133], v142
	ds_read_b128 v[134:137], v142 offset:1024
	ds_read_b128 v[138:141], v142 offset:2048
	ds_read_b128 v[142:145], v142 offset:3072
	ds_read_b128 v[174:177], v166
	ds_read_b128 v[178:181], v166 offset:1024
	ds_read_b128 v[182:185], v166 offset:2048
	ds_read_b128 v[186:189], v166 offset:3072
	s_add_u32 s48, s48, 0x40000
	s_addc_u32 s49, s49, 0
	s_mov_b32 m0, s57
	v_lshl_add_u64 v[166:167], s[48:49], 0, v[150:151]
	ds_read_b128 v[190:193], v157 offset:32768
	ds_read_b128 v[194:197], v157 offset:33792
	ds_read_b128 v[198:201], v157 offset:34816
	ds_read_b128 v[202:205], v157 offset:35840
	ds_read_b128 v[228:231], v157 offset:36864
	ds_read_b128 v[232:235], v157 offset:37888
	ds_read_b128 v[236:239], v157 offset:38912
	ds_read_b128 v[240:243], v157 offset:39936
	global_load_lds_dwordx4 v[166:167], off
	v_lshl_add_u64 v[166:167], s[48:49], 0, v[152:153]
	s_mov_b32 m0, s58
	s_nop 0
	global_load_lds_dwordx4 v[166:167], off
	s_waitcnt vmcnt(8)
	s_waitcnt lgkmcnt(0)
	s_barrier
	s_waitcnt lgkmcnt(0)
	v_mfma_f32_16x16x32_bf16 v[126:129], v[130:133], v[190:193], v[126:129]
	v_mfma_f32_16x16x32_bf16 v[122:125], v[138:141], v[190:193], v[122:125]
	v_mfma_f32_16x16x32_bf16 v[110:113], v[130:133], v[198:201], v[110:113]
	v_mfma_f32_16x16x32_bf16 v[106:109], v[138:141], v[198:201], v[106:109]
	v_mfma_f32_16x16x32_bf16 v[94:97], v[130:133], v[228:231], v[94:97]
	v_mfma_f32_16x16x32_bf16 v[90:93], v[138:141], v[228:231], v[90:93]
	v_mfma_f32_16x16x32_bf16 v[78:81], v[130:133], v[236:239], v[78:81]
	v_mfma_f32_16x16x32_bf16 v[74:77], v[138:141], v[236:239], v[74:77]
	v_mfma_f32_16x16x32_bf16 v[126:129], v[134:137], v[194:197], v[126:129]
	v_mfma_f32_16x16x32_bf16 v[122:125], v[142:145], v[194:197], v[122:125]
	v_mfma_f32_16x16x32_bf16 v[110:113], v[134:137], v[202:205], v[110:113]
	v_mfma_f32_16x16x32_bf16 v[106:109], v[142:145], v[202:205], v[106:109]
	v_mfma_f32_16x16x32_bf16 v[94:97], v[134:137], v[232:235], v[94:97]
	v_mfma_f32_16x16x32_bf16 v[90:93], v[142:145], v[232:235], v[90:93]
	v_mfma_f32_16x16x32_bf16 v[78:81], v[134:137], v[240:243], v[78:81]
	v_mfma_f32_16x16x32_bf16 v[74:77], v[142:145], v[240:243], v[74:77]
	v_mfma_f32_16x16x32_bf16 v[118:121], v[174:177], v[190:193], v[118:121]
	v_mfma_f32_16x16x32_bf16 v[114:117], v[182:185], v[190:193], v[114:117]
	v_mfma_f32_16x16x32_bf16 v[102:105], v[174:177], v[198:201], v[102:105]
	v_mfma_f32_16x16x32_bf16 v[98:101], v[182:185], v[198:201], v[98:101]
	v_mfma_f32_16x16x32_bf16 v[86:89], v[174:177], v[228:231], v[86:89]
	v_mfma_f32_16x16x32_bf16 v[82:85], v[182:185], v[228:231], v[82:85]
	v_mfma_f32_16x16x32_bf16 v[70:73], v[174:177], v[236:239], v[70:73]
	v_mfma_f32_16x16x32_bf16 v[66:69], v[182:185], v[236:239], v[66:69]
	v_mfma_f32_16x16x32_bf16 v[118:121], v[178:181], v[194:197], v[118:121]
	v_mfma_f32_16x16x32_bf16 v[114:117], v[186:189], v[194:197], v[114:117]
	v_mfma_f32_16x16x32_bf16 v[102:105], v[178:181], v[202:205], v[102:105]
	v_mfma_f32_16x16x32_bf16 v[98:101], v[186:189], v[202:205], v[98:101]
	v_mfma_f32_16x16x32_bf16 v[86:89], v[178:181], v[232:235], v[86:89]
	v_mfma_f32_16x16x32_bf16 v[82:85], v[186:189], v[232:235], v[82:85]
	v_mfma_f32_16x16x32_bf16 v[70:73], v[178:181], v[240:243], v[70:73]
	v_mfma_f32_16x16x32_bf16 v[66:69], v[186:189], v[240:243], v[66:69]
	s_barrier
	s_add_i32 s39, s39, s13
	v_lshl_add_u64 v[166:167], v[244:245], 0, s[14:15]
	s_mov_b32 m0, s39
	ds_read_b128 v[190:193], v157 offset:49152
	ds_read_b128 v[194:197], v157 offset:50176
	ds_read_b128 v[198:201], v157 offset:51200
	ds_read_b128 v[202:205], v157 offset:52224
	ds_read_b128 v[228:231], v157 offset:53248
	ds_read_b128 v[232:235], v157 offset:54272
	ds_read_b128 v[236:239], v157 offset:55296
	ds_read_b128 v[240:243], v157 offset:56320
	global_load_lds_dwordx4 v[166:167], off
	s_add_i32 m0, s39, 0x2000
	s_add_u32 s46, s46, 0x40080
	v_lshl_add_u64 v[166:167], v[246:247], 0, s[14:15]
	s_addc_u32 s47, s47, 0
	s_add_i32 s39, s43, s13
	global_load_lds_dwordx4 v[166:167], off
	v_lshl_add_u64 v[166:167], s[46:47], 0, v[0:1]
	s_mov_b32 m0, s39
	s_nop 0
	global_load_lds_dwordx4 v[166:167], off
	v_lshl_add_u64 v[166:167], s[46:47], 0, v[154:155]
	s_add_i32 m0, s39, 0x2000
	s_nop 0
	global_load_lds_dwordx4 v[166:167], off
	v_lshl_add_u64 v[166:167], v[248:249], 0, s[14:15]
	s_mov_b32 m0, s61
	s_nop 0
	global_load_lds_dwordx4 v[166:167], off
	v_lshl_add_u64 v[166:167], v[250:251], 0, s[14:15]
	s_mov_b32 m0, s62
	s_nop 0
	global_load_lds_dwordx4 v[166:167], off
	s_waitcnt vmcnt(8)
	s_waitcnt lgkmcnt(0)
	s_barrier
	s_waitcnt lgkmcnt(0)
	v_mfma_f32_16x16x32_bf16 v[62:65], v[130:133], v[190:193], v[62:65]
	v_mfma_f32_16x16x32_bf16 v[58:61], v[138:141], v[190:193], v[58:61]
	v_mfma_f32_16x16x32_bf16 v[46:49], v[130:133], v[198:201], v[46:49]
	v_mfma_f32_16x16x32_bf16 v[42:45], v[138:141], v[198:201], v[42:45]
	v_mfma_f32_16x16x32_bf16 v[30:33], v[130:133], v[228:231], v[30:33]
	v_mfma_f32_16x16x32_bf16 v[26:29], v[138:141], v[228:231], v[26:29]
	v_mfma_f32_16x16x32_bf16 v[14:17], v[130:133], v[236:239], v[14:17]
	v_mfma_f32_16x16x32_bf16 v[10:13], v[138:141], v[236:239], v[10:13]
	v_mfma_f32_16x16x32_bf16 v[62:65], v[134:137], v[194:197], v[62:65]
	v_mfma_f32_16x16x32_bf16 v[58:61], v[142:145], v[194:197], v[58:61]
	v_mfma_f32_16x16x32_bf16 v[46:49], v[134:137], v[202:205], v[46:49]
	v_mfma_f32_16x16x32_bf16 v[42:45], v[142:145], v[202:205], v[42:45]
	v_mfma_f32_16x16x32_bf16 v[30:33], v[134:137], v[232:235], v[30:33]
	v_mfma_f32_16x16x32_bf16 v[26:29], v[142:145], v[232:235], v[26:29]
	v_mfma_f32_16x16x32_bf16 v[14:17], v[134:137], v[240:243], v[14:17]
	v_mfma_f32_16x16x32_bf16 v[10:13], v[142:145], v[240:243], v[10:13]
	v_mfma_f32_16x16x32_bf16 v[54:57], v[174:177], v[190:193], v[54:57]
	v_mfma_f32_16x16x32_bf16 v[50:53], v[182:185], v[190:193], v[50:53]
	v_mfma_f32_16x16x32_bf16 v[38:41], v[174:177], v[198:201], v[38:41]
	v_mfma_f32_16x16x32_bf16 v[34:37], v[182:185], v[198:201], v[34:37]
	v_mfma_f32_16x16x32_bf16 v[22:25], v[174:177], v[228:231], v[22:25]
	v_mfma_f32_16x16x32_bf16 v[18:21], v[182:185], v[228:231], v[18:21]
	v_mfma_f32_16x16x32_bf16 v[6:9], v[174:177], v[236:239], v[6:9]
	v_mfma_f32_16x16x32_bf16 v[2:5], v[182:185], v[236:239], v[2:5]
	v_mfma_f32_16x16x32_bf16 v[54:57], v[178:181], v[194:197], v[54:57]
	v_mfma_f32_16x16x32_bf16 v[50:53], v[186:189], v[194:197], v[50:53]
	v_mfma_f32_16x16x32_bf16 v[38:41], v[178:181], v[202:205], v[38:41]
	v_mfma_f32_16x16x32_bf16 v[34:37], v[186:189], v[202:205], v[34:37]
	v_mfma_f32_16x16x32_bf16 v[22:25], v[178:181], v[232:235], v[22:25]
	v_mfma_f32_16x16x32_bf16 v[18:21], v[186:189], v[232:235], v[18:21]
	v_mfma_f32_16x16x32_bf16 v[6:9], v[178:181], v[240:243], v[6:9]
	v_mfma_f32_16x16x32_bf16 v[2:5], v[186:189], v[240:243], v[2:5]
	s_barrier
	s_add_i32 s34, s34, 2
	s_add_u32 s44, s44, 0x100
	s_addc_u32 s45, s45, 0
	s_add_u32 s27, s27, 0x100
	s_addc_u32 s29, s29, 0
	s_cmp_gt_u32 s34, 13
	s_cbranch_scc1 .Lpeel_k1067_exit
.LBB0_1067:
	s_add_u32 s39, s44, 0xfffc0080
	s_addc_u32 s43, s45, -1
	s_add_i32 s50, 0, 0x10000
	s_cmp_eq_u32 s34, 12
	s_cselect_b32 s49, s21, s43
	s_cselect_b32 s48, s23, s39
	s_cselect_b32 s47, s19, s29
	s_cselect_b32 s46, s26, s27
	s_add_i32 s39, 0, 0x14000
	v_add_u32_e32 v142, s50, v222
	v_add_u32_e32 v166, s39, v222
	ds_read_b128 v[130:133], v142
	ds_read_b128 v[134:137], v142 offset:1024
	ds_read_b128 v[138:141], v142 offset:2048
	ds_read_b128 v[142:145], v142 offset:3072
	s_waitcnt lgkmcnt(0)
	ds_read_b128 v[174:177], v166
	ds_read_b128 v[178:181], v166 offset:1024
	ds_read_b128 v[182:185], v166 offset:2048
	ds_read_b128 v[186:189], v166 offset:3072
	v_lshl_add_u64 v[244:245], s[44:45], 0, v[162:163]
	s_add_i32 m0, s55, 0xc000
	ds_read_b128 v[190:193], v157
	ds_read_b128 v[194:197], v157 offset:1024
	ds_read_b128 v[198:201], v157 offset:2048
	ds_read_b128 v[202:205], v157 offset:3072
	ds_read_b128 v[228:231], v157 offset:4096
	ds_read_b128 v[232:235], v157 offset:5120
	ds_read_b128 v[236:239], v157 offset:6144
	ds_read_b128 v[240:243], v157 offset:7168
	global_load_lds_dwordx4 v[244:245], off
	v_lshl_add_u64 v[244:245], s[44:45], 0, v[164:165]
	s_add_i32 m0, s55, 0xe000
	s_nop 0
	global_load_lds_dwordx4 v[244:245], off
	s_waitcnt vmcnt(8)
	s_waitcnt lgkmcnt(0)
	s_barrier
	s_waitcnt lgkmcnt(0)
	v_mfma_f32_16x16x32_bf16 v[126:129], v[130:133], v[190:193], v[126:129]
	v_mfma_f32_16x16x32_bf16 v[122:125], v[138:141], v[190:193], v[122:125]
	v_mfma_f32_16x16x32_bf16 v[110:113], v[130:133], v[198:201], v[110:113]
	v_mfma_f32_16x16x32_bf16 v[106:109], v[138:141], v[198:201], v[106:109]
	v_mfma_f32_16x16x32_bf16 v[94:97], v[130:133], v[228:231], v[94:97]
	v_mfma_f32_16x16x32_bf16 v[90:93], v[138:141], v[228:231], v[90:93]
	v_mfma_f32_16x16x32_bf16 v[78:81], v[130:133], v[236:239], v[78:81]
	v_mfma_f32_16x16x32_bf16 v[74:77], v[138:141], v[236:239], v[74:77]
	v_mfma_f32_16x16x32_bf16 v[126:129], v[134:137], v[194:197], v[126:129]
	v_mfma_f32_16x16x32_bf16 v[122:125], v[142:145], v[194:197], v[122:125]
	v_mfma_f32_16x16x32_bf16 v[110:113], v[134:137], v[202:205], v[110:113]
	v_mfma_f32_16x16x32_bf16 v[106:109], v[142:145], v[202:205], v[106:109]
	v_mfma_f32_16x16x32_bf16 v[94:97], v[134:137], v[232:235], v[94:97]
	v_mfma_f32_16x16x32_bf16 v[90:93], v[142:145], v[232:235], v[90:93]
	v_mfma_f32_16x16x32_bf16 v[78:81], v[134:137], v[240:243], v[78:81]
	v_mfma_f32_16x16x32_bf16 v[74:77], v[142:145], v[240:243], v[74:77]
	v_mfma_f32_16x16x32_bf16 v[118:121], v[174:177], v[190:193], v[118:121]
	v_mfma_f32_16x16x32_bf16 v[114:117], v[182:185], v[190:193], v[114:117]
	v_mfma_f32_16x16x32_bf16 v[102:105], v[174:177], v[198:201], v[102:105]
	v_mfma_f32_16x16x32_bf16 v[98:101], v[182:185], v[198:201], v[98:101]
	v_mfma_f32_16x16x32_bf16 v[86:89], v[174:177], v[228:231], v[86:89]
	v_mfma_f32_16x16x32_bf16 v[82:85], v[182:185], v[228:231], v[82:85]
	v_mfma_f32_16x16x32_bf16 v[70:73], v[174:177], v[236:239], v[70:73]
	v_mfma_f32_16x16x32_bf16 v[66:69], v[182:185], v[236:239], v[66:69]
	v_mfma_f32_16x16x32_bf16 v[118:121], v[178:181], v[194:197], v[118:121]
	v_mfma_f32_16x16x32_bf16 v[114:117], v[186:189], v[194:197], v[114:117]
	v_mfma_f32_16x16x32_bf16 v[102:105], v[178:181], v[202:205], v[102:105]
	v_mfma_f32_16x16x32_bf16 v[98:101], v[186:189], v[202:205], v[98:101]
	v_mfma_f32_16x16x32_bf16 v[86:89], v[178:181], v[232:235], v[86:89]
	v_mfma_f32_16x16x32_bf16 v[82:85], v[186:189], v[232:235], v[82:85]
	v_mfma_f32_16x16x32_bf16 v[70:73], v[178:181], v[240:243], v[70:73]
	v_mfma_f32_16x16x32_bf16 v[66:69], v[186:189], v[240:243], v[66:69]
	s_barrier
	s_add_i32 s43, s50, s13
	v_lshl_add_u64 v[244:245], s[46:47], 0, v[0:1]
	s_mov_b32 m0, s43
	ds_read_b128 v[190:193], v157 offset:16384
	ds_read_b128 v[194:197], v157 offset:17408
	ds_read_b128 v[198:201], v157 offset:18432
	ds_read_b128 v[202:205], v157 offset:19456
	ds_read_b128 v[228:231], v157 offset:20480
	ds_read_b128 v[232:235], v157 offset:21504
	ds_read_b128 v[236:239], v157 offset:22528
	ds_read_b128 v[240:243], v157 offset:23552
	global_load_lds_dwordx4 v[244:245], off
	s_add_i32 m0, s43, 0x2000
	s_add_u32 s50, s46, 0x40000
	v_lshl_add_u64 v[246:247], s[46:47], 0, v[154:155]
	s_addc_u32 s51, s47, 0
	s_add_i32 s39, s39, s13
	global_load_lds_dwordx4 v[246:247], off
	v_lshl_add_u64 v[248:249], s[50:51], 0, v[0:1]
	s_mov_b32 m0, s39
	v_lshl_add_u64 v[250:251], s[48:49], 0, v[152:153]
	global_load_lds_dwordx4 v[248:249], off
	v_lshl_add_u64 v[248:249], s[50:51], 0, v[154:155]
	s_add_i32 m0, s39, 0x2000
	s_nop 0
	global_load_lds_dwordx4 v[248:249], off
	v_lshl_add_u64 v[248:249], s[48:49], 0, v[150:151]
	s_mov_b32 m0, s55
	s_nop 0
	global_load_lds_dwordx4 v[248:249], off
	s_mov_b32 m0, s56
	s_nop 0
	global_load_lds_dwordx4 v[250:251], off
	s_waitcnt vmcnt(8)
	s_waitcnt lgkmcnt(0)
	s_barrier
	s_waitcnt lgkmcnt(0)
	v_mfma_f32_16x16x32_bf16 v[62:65], v[130:133], v[190:193], v[62:65]
	v_mfma_f32_16x16x32_bf16 v[58:61], v[138:141], v[190:193], v[58:61]
	v_mfma_f32_16x16x32_bf16 v[46:49], v[130:133], v[198:201], v[46:49]
	v_mfma_f32_16x16x32_bf16 v[42:45], v[138:141], v[198:201], v[42:45]
	v_mfma_f32_16x16x32_bf16 v[30:33], v[130:133], v[228:231], v[30:33]
	v_mfma_f32_16x16x32_bf16 v[26:29], v[138:141], v[228:231], v[26:29]
	v_mfma_f32_16x16x32_bf16 v[14:17], v[130:133], v[236:239], v[14:17]
	v_mfma_f32_16x16x32_bf16 v[10:13], v[138:141], v[236:239], v[10:13]
	v_mfma_f32_16x16x32_bf16 v[62:65], v[134:137], v[194:197], v[62:65]
	v_mfma_f32_16x16x32_bf16 v[58:61], v[142:145], v[194:197], v[58:61]
	v_mfma_f32_16x16x32_bf16 v[46:49], v[134:137], v[202:205], v[46:49]
	v_mfma_f32_16x16x32_bf16 v[42:45], v[142:145], v[202:205], v[42:45]
	v_mfma_f32_16x16x32_bf16 v[30:33], v[134:137], v[232:235], v[30:33]
	v_mfma_f32_16x16x32_bf16 v[26:29], v[142:145], v[232:235], v[26:29]
	v_mfma_f32_16x16x32_bf16 v[14:17], v[134:137], v[240:243], v[14:17]
	v_mfma_f32_16x16x32_bf16 v[10:13], v[142:145], v[240:243], v[10:13]
	v_mfma_f32_16x16x32_bf16 v[54:57], v[174:177], v[190:193], v[54:57]
	v_mfma_f32_16x16x32_bf16 v[50:53], v[182:185], v[190:193], v[50:53]
	v_mfma_f32_16x16x32_bf16 v[38:41], v[174:177], v[198:201], v[38:41]
	v_mfma_f32_16x16x32_bf16 v[34:37], v[182:185], v[198:201], v[34:37]
	v_mfma_f32_16x16x32_bf16 v[22:25], v[174:177], v[228:231], v[22:25]
	v_mfma_f32_16x16x32_bf16 v[18:21], v[182:185], v[228:231], v[18:21]
	v_mfma_f32_16x16x32_bf16 v[6:9], v[174:177], v[236:239], v[6:9]
	v_mfma_f32_16x16x32_bf16 v[2:5], v[182:185], v[236:239], v[2:5]
	v_mfma_f32_16x16x32_bf16 v[54:57], v[178:181], v[194:197], v[54:57]
	v_mfma_f32_16x16x32_bf16 v[50:53], v[186:189], v[194:197], v[50:53]
	v_mfma_f32_16x16x32_bf16 v[38:41], v[178:181], v[202:205], v[38:41]
	v_mfma_f32_16x16x32_bf16 v[34:37], v[186:189], v[202:205], v[34:37]
	v_mfma_f32_16x16x32_bf16 v[22:25], v[178:181], v[232:235], v[22:25]
	v_mfma_f32_16x16x32_bf16 v[18:21], v[186:189], v[232:235], v[18:21]
	v_mfma_f32_16x16x32_bf16 v[6:9], v[178:181], v[240:243], v[6:9]
	v_mfma_f32_16x16x32_bf16 v[2:5], v[186:189], v[240:243], v[2:5]
	s_barrier
	s_add_i32 s39, 0, 0x18000
	s_add_i32 s43, 0, 0x1c000
	v_add_u32_e32 v142, s39, v222
	v_add_u32_e32 v166, s43, v222
	ds_read_b128 v[130:133], v142
	ds_read_b128 v[134:137], v142 offset:1024
	ds_read_b128 v[138:141], v142 offset:2048
	ds_read_b128 v[142:145], v142 offset:3072
	ds_read_b128 v[174:177], v166
	ds_read_b128 v[178:181], v166 offset:1024
	ds_read_b128 v[182:185], v166 offset:2048
	ds_read_b128 v[186:189], v166 offset:3072
	s_add_u32 s48, s48, 0x40000
	s_addc_u32 s49, s49, 0
	s_mov_b32 m0, s57
	v_lshl_add_u64 v[166:167], s[48:49], 0, v[150:151]
	ds_read_b128 v[190:193], v157 offset:32768
	ds_read_b128 v[194:197], v157 offset:33792
	ds_read_b128 v[198:201], v157 offset:34816
	ds_read_b128 v[202:205], v157 offset:35840
	ds_read_b128 v[228:231], v157 offset:36864
	ds_read_b128 v[232:235], v157 offset:37888
	ds_read_b128 v[236:239], v157 offset:38912
	ds_read_b128 v[240:243], v157 offset:39936
	global_load_lds_dwordx4 v[166:167], off
	v_lshl_add_u64 v[166:167], s[48:49], 0, v[152:153]
	s_mov_b32 m0, s58
	s_nop 0
	global_load_lds_dwordx4 v[166:167], off
	s_waitcnt vmcnt(8)
	s_waitcnt lgkmcnt(0)
	s_barrier
	s_waitcnt lgkmcnt(0)
	v_mfma_f32_16x16x32_bf16 v[126:129], v[130:133], v[190:193], v[126:129]
	v_mfma_f32_16x16x32_bf16 v[122:125], v[138:141], v[190:193], v[122:125]
	v_mfma_f32_16x16x32_bf16 v[110:113], v[130:133], v[198:201], v[110:113]
	v_mfma_f32_16x16x32_bf16 v[106:109], v[138:141], v[198:201], v[106:109]
	v_mfma_f32_16x16x32_bf16 v[94:97], v[130:133], v[228:231], v[94:97]
	v_mfma_f32_16x16x32_bf16 v[90:93], v[138:141], v[228:231], v[90:93]
	v_mfma_f32_16x16x32_bf16 v[78:81], v[130:133], v[236:239], v[78:81]
	v_mfma_f32_16x16x32_bf16 v[74:77], v[138:141], v[236:239], v[74:77]
	v_mfma_f32_16x16x32_bf16 v[126:129], v[134:137], v[194:197], v[126:129]
	v_mfma_f32_16x16x32_bf16 v[122:125], v[142:145], v[194:197], v[122:125]
	v_mfma_f32_16x16x32_bf16 v[110:113], v[134:137], v[202:205], v[110:113]
	v_mfma_f32_16x16x32_bf16 v[106:109], v[142:145], v[202:205], v[106:109]
	v_mfma_f32_16x16x32_bf16 v[94:97], v[134:137], v[232:235], v[94:97]
	v_mfma_f32_16x16x32_bf16 v[90:93], v[142:145], v[232:235], v[90:93]
	v_mfma_f32_16x16x32_bf16 v[78:81], v[134:137], v[240:243], v[78:81]
	v_mfma_f32_16x16x32_bf16 v[74:77], v[142:145], v[240:243], v[74:77]
	v_mfma_f32_16x16x32_bf16 v[118:121], v[174:177], v[190:193], v[118:121]
	v_mfma_f32_16x16x32_bf16 v[114:117], v[182:185], v[190:193], v[114:117]
	v_mfma_f32_16x16x32_bf16 v[102:105], v[174:177], v[198:201], v[102:105]
	v_mfma_f32_16x16x32_bf16 v[98:101], v[182:185], v[198:201], v[98:101]
	v_mfma_f32_16x16x32_bf16 v[86:89], v[174:177], v[228:231], v[86:89]
	v_mfma_f32_16x16x32_bf16 v[82:85], v[182:185], v[228:231], v[82:85]
	v_mfma_f32_16x16x32_bf16 v[70:73], v[174:177], v[236:239], v[70:73]
	v_mfma_f32_16x16x32_bf16 v[66:69], v[182:185], v[236:239], v[66:69]
	v_mfma_f32_16x16x32_bf16 v[118:121], v[178:181], v[194:197], v[118:121]
	v_mfma_f32_16x16x32_bf16 v[114:117], v[186:189], v[194:197], v[114:117]
	v_mfma_f32_16x16x32_bf16 v[102:105], v[178:181], v[202:205], v[102:105]
	v_mfma_f32_16x16x32_bf16 v[98:101], v[186:189], v[202:205], v[98:101]
	v_mfma_f32_16x16x32_bf16 v[86:89], v[178:181], v[232:235], v[86:89]
	v_mfma_f32_16x16x32_bf16 v[82:85], v[186:189], v[232:235], v[82:85]
	v_mfma_f32_16x16x32_bf16 v[70:73], v[178:181], v[240:243], v[70:73]
	v_mfma_f32_16x16x32_bf16 v[66:69], v[186:189], v[240:243], v[66:69]
	s_barrier
	s_add_i32 s39, s39, s13
	v_lshl_add_u64 v[166:167], v[244:245], 0, s[14:15]
	s_mov_b32 m0, s39
	ds_read_b128 v[190:193], v157 offset:49152
	ds_read_b128 v[194:197], v157 offset:50176
	ds_read_b128 v[198:201], v157 offset:51200
	ds_read_b128 v[202:205], v157 offset:52224
	ds_read_b128 v[228:231], v157 offset:53248
	ds_read_b128 v[232:235], v157 offset:54272
	ds_read_b128 v[236:239], v157 offset:55296
	ds_read_b128 v[240:243], v157 offset:56320
	global_load_lds_dwordx4 v[166:167], off
	s_add_i32 m0, s39, 0x2000
	s_add_u32 s46, s46, 0x40080
	v_lshl_add_u64 v[166:167], v[246:247], 0, s[14:15]
	s_addc_u32 s47, s47, 0
	s_add_i32 s39, s43, s13
	global_load_lds_dwordx4 v[166:167], off
	v_lshl_add_u64 v[166:167], s[46:47], 0, v[0:1]
	s_mov_b32 m0, s39
	s_nop 0
	global_load_lds_dwordx4 v[166:167], off
	v_lshl_add_u64 v[166:167], s[46:47], 0, v[154:155]
	s_add_i32 m0, s39, 0x2000
	s_nop 0
	global_load_lds_dwordx4 v[166:167], off
	v_lshl_add_u64 v[166:167], v[248:249], 0, s[14:15]
	s_mov_b32 m0, s61
	s_nop 0
	global_load_lds_dwordx4 v[166:167], off
	v_lshl_add_u64 v[166:167], v[250:251], 0, s[14:15]
	s_mov_b32 m0, s62
	s_nop 0
	global_load_lds_dwordx4 v[166:167], off
	s_waitcnt vmcnt(8)
	s_waitcnt lgkmcnt(0)
	s_barrier
	s_waitcnt lgkmcnt(0)
	v_mfma_f32_16x16x32_bf16 v[62:65], v[130:133], v[190:193], v[62:65]
	v_mfma_f32_16x16x32_bf16 v[58:61], v[138:141], v[190:193], v[58:61]
	v_mfma_f32_16x16x32_bf16 v[46:49], v[130:133], v[198:201], v[46:49]
	v_mfma_f32_16x16x32_bf16 v[42:45], v[138:141], v[198:201], v[42:45]
	v_mfma_f32_16x16x32_bf16 v[30:33], v[130:133], v[228:231], v[30:33]
	v_mfma_f32_16x16x32_bf16 v[26:29], v[138:141], v[228:231], v[26:29]
	v_mfma_f32_16x16x32_bf16 v[14:17], v[130:133], v[236:239], v[14:17]
	v_mfma_f32_16x16x32_bf16 v[10:13], v[138:141], v[236:239], v[10:13]
	v_mfma_f32_16x16x32_bf16 v[62:65], v[134:137], v[194:197], v[62:65]
	v_mfma_f32_16x16x32_bf16 v[58:61], v[142:145], v[194:197], v[58:61]
	v_mfma_f32_16x16x32_bf16 v[46:49], v[134:137], v[202:205], v[46:49]
	v_mfma_f32_16x16x32_bf16 v[42:45], v[142:145], v[202:205], v[42:45]
	v_mfma_f32_16x16x32_bf16 v[30:33], v[134:137], v[232:235], v[30:33]
	v_mfma_f32_16x16x32_bf16 v[26:29], v[142:145], v[232:235], v[26:29]
	v_mfma_f32_16x16x32_bf16 v[14:17], v[134:137], v[240:243], v[14:17]
	v_mfma_f32_16x16x32_bf16 v[10:13], v[142:145], v[240:243], v[10:13]
	v_mfma_f32_16x16x32_bf16 v[54:57], v[174:177], v[190:193], v[54:57]
	v_mfma_f32_16x16x32_bf16 v[50:53], v[182:185], v[190:193], v[50:53]
	v_mfma_f32_16x16x32_bf16 v[38:41], v[174:177], v[198:201], v[38:41]
	v_mfma_f32_16x16x32_bf16 v[34:37], v[182:185], v[198:201], v[34:37]
	v_mfma_f32_16x16x32_bf16 v[22:25], v[174:177], v[228:231], v[22:25]
	v_mfma_f32_16x16x32_bf16 v[18:21], v[182:185], v[228:231], v[18:21]
	v_mfma_f32_16x16x32_bf16 v[6:9], v[174:177], v[236:239], v[6:9]
	v_mfma_f32_16x16x32_bf16 v[2:5], v[182:185], v[236:239], v[2:5]
	v_mfma_f32_16x16x32_bf16 v[54:57], v[178:181], v[194:197], v[54:57]
	v_mfma_f32_16x16x32_bf16 v[50:53], v[186:189], v[194:197], v[50:53]
	v_mfma_f32_16x16x32_bf16 v[38:41], v[178:181], v[202:205], v[38:41]
	v_mfma_f32_16x16x32_bf16 v[34:37], v[186:189], v[202:205], v[34:37]
	v_mfma_f32_16x16x32_bf16 v[22:25], v[178:181], v[232:235], v[22:25]
	v_mfma_f32_16x16x32_bf16 v[18:21], v[186:189], v[232:235], v[18:21]
	v_mfma_f32_16x16x32_bf16 v[6:9], v[178:181], v[240:243], v[6:9]
	v_mfma_f32_16x16x32_bf16 v[2:5], v[186:189], v[240:243], v[2:5]
	s_barrier
	s_add_i32 s34, s34, 2
	s_add_u32 s44, s44, 0x100
	s_addc_u32 s45, s45, 0
	s_add_u32 s27, s27, 0x100
	s_addc_u32 s29, s29, 0
	s_cmp_gt_u32 s34, 13
	s_cbranch_scc0 .LBB0_1067
